# PEER expert phase, quad lane mapping: 4 lanes per 192-B row slice, three aligned dwordx4 loads per two conversion units, U dot products with v_dot2_f32_bf16 on exact bf16 copies of the fp6 values
# speedup vs baseline: 1.1717x; 1.0007x over previous
.LBB0_130:
	v_mov_b32_e32 v16, v186
	v_readlane_b32 s4, v242, 0
	v_ashrrev_i32_e32 v17, 6, v16
	s_nop 0
	v_add_u32_e32 v17, s4, v17
	s_nop 0
	v_readfirstlane_b32 s10, v17
	s_cmpk_gt_i32 s10, 0x7fff
	s_cbranch_scc1 .LBB0_99
	s_load_dword s4, s[80:81], 0x10
	v_and_b32_e32 v17, 63, v16
	v_lshlrev_b32_e32 v16, 2, v17
	v_lshrrev_b32_e32 v36, 3, v17
	v_mul_u32_u24_e32 v36, 3, v36
	v_lshlrev_b32_e32 v36, 20, v36
	v_bfe_u32 v37, v17, 1, 2
	v_lshl_add_u32 v36, v37, 4, v36
	v_and_b32_e32 v37, 1, v17
	v_lshl_add_u32 v32, v37, 7, v36
	v_lshl_add_u32 v34, v37, 3, v36
	v_add_u32_e32 v34, 64, v34
	s_waitcnt lgkmcnt(0)
	s_lshr_b32 s4, s4, 16
	s_cmp_lg_u32 s4, 0
	s_cselect_b64 s[4:5], -1, 0
	s_cmp_lg_u64 s[4:5], 0
	s_addc_u32 s4, s78, 0
	s_lshl_b32 s11, s4, 3
	v_cmp_eq_u32_e64 s[4:5], 0, v17
	v_xor_b32_e32 v17, 1, v179
	v_cmp_lt_i32_e32 vcc, v17, v151
	v_mov_b32_e32 v33, v177
	v_mov_b32_e32 v35, v177
	v_cndmask_b32_e32 v17, v179, v17, vcc
	v_lshlrev_b32_e32 v36, 2, v17
	v_xor_b32_e32 v17, 2, v179
	v_cmp_lt_i32_e32 vcc, v17, v151
	v_lshlrev_b32_e32 v176, 2, v16
	s_nop 0
	v_cndmask_b32_e32 v17, v179, v17, vcc
	v_lshlrev_b32_e32 v37, 2, v17
	v_xor_b32_e32 v17, 4, v179
	v_cmp_lt_i32_e32 vcc, v17, v151
	s_nop 1
	v_cndmask_b32_e32 v17, v179, v17, vcc
	v_lshlrev_b32_e32 v38, 2, v17
	v_xor_b32_e32 v17, 8, v179
	v_cmp_lt_i32_e32 vcc, v17, v151
	s_nop 1
	v_cndmask_b32_e32 v17, v179, v17, vcc
	v_lshlrev_b32_e32 v39, 2, v17
	v_xor_b32_e32 v17, 16, v179
	v_cmp_lt_i32_e32 vcc, v17, v151
	s_nop 1
	v_cndmask_b32_e32 v17, v179, v17, vcc
	v_lshlrev_b32_e32 v40, 2, v17
	s_branch .LBB0_133

.LBB0_133:
	s_and_b32 s12, s10, 0x3fff
	s_lshl_b32 s13, s12, 13
	s_cmpk_gt_i32 s10, 0x3fff
	s_cselect_b64 s[6:7], -1, 0
	s_and_b64 s[8:9], s[6:7], exec
	s_cselect_b32 s14, s66, s64
	s_cselect_b32 s15, s67, s65
	s_cselect_b32 s8, s71, s69
	s_cselect_b32 s9, s70, s68
	s_add_u32 s14, s14, s13
	s_addc_u32 s15, s15, 0
	v_lshl_add_u64 v[42:43], s[14:15], 0, v[176:177]
	global_load_dwordx4 v[16:19], v176, s[14:15]
	global_load_dwordx4 v[20:23], v176, s[14:15] offset:1024
	global_load_dwordx4 v[24:27], v176, s[14:15] offset:2048
	global_load_dwordx4 v[28:31], v176, s[14:15] offset:3072
	v_add_co_u32_e32 v54, vcc, s92, v42
	s_mul_i32 s13, s12, 0xc0
	s_nop 0
	v_addc_co_u32_e32 v55, vcc, 0, v43, vcc
	global_load_dwordx4 v[42:45], v[54:55], off
	global_load_dwordx4 v[46:49], v[54:55], off offset:1024
	global_load_dwordx4 v[50:53], v[54:55], off offset:2048
	s_nop 0
	global_load_dwordx4 v[54:57], v[54:55], off offset:3072
	s_waitcnt vmcnt(7)
	v_max_f32_e64 v41, |v19|, |v19|
	v_max_f32_e64 v58, |v18|, |v18|
	s_waitcnt vmcnt(6)
	v_max_f32_e64 v59, |v23|, |v23|
	v_max_f32_e64 v60, |v22|, |v22|
	s_waitcnt vmcnt(5)
	v_max_f32_e64 v61, |v27|, |v27|
	v_max_f32_e64 v62, |v26|, |v26|
	s_waitcnt vmcnt(4)
	v_max_f32_e64 v63, |v31|, |v31|
	v_max_f32_e64 v64, |v30|, |v30|
	v_max_f32_e32 v41, v58, v41
	v_max_f32_e32 v58, v60, v59
	v_max_f32_e32 v59, v62, v61
	v_max_f32_e32 v60, v64, v63
	v_max3_f32 v41, |v16|, |v17|, v41
	v_max3_f32 v58, |v20|, |v21|, v58
	s_waitcnt vmcnt(3)
	v_max_f32_e64 v61, |v45|, |v45|
	v_max_f32_e64 v62, |v44|, |v44|
	s_waitcnt vmcnt(2)
	v_max_f32_e64 v63, |v49|, |v49|
	v_max_f32_e64 v64, |v48|, |v48|
	v_max3_f32 v59, |v24|, |v25|, v59
	v_max3_f32 v60, |v28|, |v29|, v60
	s_waitcnt vmcnt(1)
	v_max_f32_e64 v65, |v53|, |v53|
	v_max_f32_e64 v66, |v52|, |v52|
	s_waitcnt vmcnt(0)
	v_max_f32_e64 v67, |v57|, |v57|
	v_max_f32_e64 v68, |v56|, |v56|
	v_max3_f32 v41, v41, 0, v58
	v_max_f32_e32 v58, v62, v61
	v_max_f32_e32 v61, v64, v63
	v_max_f32_e32 v62, v66, v65
	v_max_f32_e32 v63, v68, v67
	v_max3_f32 v41, v41, v59, v60
	v_max3_f32 v58, |v42|, |v43|, v58
	v_max3_f32 v59, |v46|, |v47|, v61
	v_max3_f32 v60, |v50|, |v51|, v62
	v_max3_f32 v61, |v54|, |v55|, v63
	v_max3_f32 v41, v41, v58, v59
	v_max3_f32 v41, v41, v60, v61
	ds_bpermute_b32 v58, v36, v41
	v_mov_b32_e32 v59, v18
	v_pk_mov_b32 v[18:19], v[18:19], v[20:21] op_sel:[1,0]
	v_mov_b32_e32 v20, v21
	v_mov_b32_e32 v21, v22
	s_waitcnt lgkmcnt(0)
	v_max_f32_e32 v58, v58, v58
	v_max_f32_e32 v41, v41, v58
	ds_bpermute_b32 v60, v37, v41
	v_mov_b32_e32 v58, v17
	v_pk_mov_b32 v[22:23], v[22:23], v[24:25] op_sel:[1,0]
	v_mov_b32_e32 v24, v25
	s_waitcnt lgkmcnt(0)
	v_max_f32_e32 v17, v60, v60
	v_max_f32_e32 v17, v41, v17
	ds_bpermute_b32 v41, v38, v17
	s_waitcnt lgkmcnt(0)
	v_max_f32_e32 v25, v41, v41
	v_max_f32_e32 v17, v17, v25
	ds_bpermute_b32 v41, v39, v17
	v_mov_b32_e32 v25, v26
	v_pk_mov_b32 v[26:27], v[26:27], v[28:29] op_sel:[1,0]
	v_mov_b32_e32 v28, v29
	v_mov_b32_e32 v29, v30
	s_waitcnt lgkmcnt(0)
	v_max_f32_e32 v30, v41, v41
	v_max_f32_e32 v17, v17, v30
	ds_bpermute_b32 v41, v40, v17
	v_pk_mov_b32 v[30:31], v[30:31], v[42:43] op_sel:[1,0]
	v_mov_b32_e32 v42, v43
	v_mov_b32_e32 v43, v44
	v_pk_mov_b32 v[44:45], v[44:45], v[46:47] op_sel:[1,0]
	s_waitcnt lgkmcnt(0)
	v_max_f32_e32 v41, v41, v41
	v_max_f32_e32 v17, v17, v41
	ds_bpermute_b32 v41, v150, v17
	v_mov_b32_e32 v46, v47
	v_mov_b32_e32 v47, v48
	v_pk_mov_b32 v[48:49], v[48:49], v[50:51] op_sel:[1,0]
	v_mov_b32_e32 v50, v51
	s_waitcnt lgkmcnt(0)
	v_max_f32_e32 v41, v41, v41
	v_max_f32_e32 v41, v17, v41
	v_div_scale_f32 v17, s[14:15], v41, v41, s94
	v_rcp_f32_e32 v60, v17
	v_mov_b32_e32 v51, v52
	v_div_scale_f32 v52, vcc, s94, v41, s94
	v_fma_f32 v61, -v17, v60, 1.0
	v_fmac_f32_e32 v60, v61, v60
	v_mul_f32_e32 v61, v52, v60
	v_fma_f32 v62, -v17, v61, v52
	v_fmac_f32_e32 v61, v62, v60
	v_fma_f32 v17, -v17, v61, v52
	v_div_fmas_f32 v17, v17, v60, v61
	v_div_fixup_f32 v17, v17, v41, s94
	v_cmp_lt_f32_e32 vcc, 0, v41
	s_add_u32 s14, s9, s13
	s_addc_u32 s15, s8, 0
	v_cndmask_b32_e32 v52, 1.0, v17, vcc
	v_pk_mul_f32 v[18:19], v[18:19], v[52:53] op_sel_hi:[1,0]
	v_pk_mul_f32 v[20:21], v[20:21], v[52:53] op_sel_hi:[1,0]
	v_pk_mul_f32 v[24:25], v[24:25], v[52:53] op_sel_hi:[1,0]
	v_pk_mul_f32 v[30:31], v[30:31], v[52:53] op_sel_hi:[1,0]
	v_cvt_pk_f16_f32 v18, v18, v19
	v_cvt_pk_f16_f32 v19, v20, v21
	v_cvt_pk_f16_f32 v21, v24, v25
	v_cvt_pk_f16_f32 v24, v30, v31
	v_pk_mov_b32 v[30:31], v[52:53], v[54:55] op_sel:[1,0]
	v_pk_mul_f32 v[42:43], v[42:43], v[52:53] op_sel_hi:[1,0]
	v_pk_mul_f32 v[30:31], v[30:31], v[52:53] op_sel_hi:[1,0]
	v_cvt_pk_f16_f32 v25, v42, v43
	v_cvt_pk_f16_f32 v42, v30, v31
	v_mov_b32_e32 v30, v55
	v_mov_b32_e32 v31, v56
	v_pk_mul_f32 v[30:31], v[30:31], v[52:53] op_sel_hi:[1,0]
	v_fma_mixlo_f16 v60, v16, v52, 0
	v_pk_mul_f32 v[16:17], v[58:59], v[52:53] op_sel_hi:[1,0]
	v_pk_mul_f32 v[22:23], v[22:23], v[52:53] op_sel_hi:[1,0]
	v_pk_mul_f32 v[26:27], v[26:27], v[52:53] op_sel_hi:[1,0]
	v_pk_mul_f32 v[28:29], v[28:29], v[52:53] op_sel_hi:[1,0]
	v_pk_mul_f32 v[44:45], v[44:45], v[52:53] op_sel_hi:[1,0]
	v_pk_mul_f32 v[46:47], v[46:47], v[52:53] op_sel_hi:[1,0]
	v_pk_mul_f32 v[48:49], v[48:49], v[52:53] op_sel_hi:[1,0]
	v_pk_mul_f32 v[50:51], v[50:51], v[52:53] op_sel_hi:[1,0]
	v_cvt_pk_f16_f32 v31, v30, v31
	v_cvt_pk_f16_f32 v17, v16, v17
	v_cvt_pk_f16_f32 v20, v22, v23
	v_cvt_pk_f16_f32 v22, v26, v27
	v_cvt_pk_f16_f32 v23, v28, v29
	v_cvt_pk_f16_f32 v26, v44, v45
	v_cvt_pk_f16_f32 v27, v46, v47
	v_cvt_pk_f16_f32 v28, v48, v49
	v_cvt_pk_f16_f32 v29, v50, v51
	v_alignbit_b32 v30, v31, v42, 16
	v_lshrrev_b32_e32 v31, 16, v31
	v_pack_b32_f16 v16, v60, v17
	v_alignbit_b32 v17, v18, v17, 16
	v_alignbit_b32 v18, v19, v18, 16
	v_alignbit_b32 v19, v20, v19, 16
	v_alignbit_b32 v20, v21, v20, 16
	v_alignbit_b32 v21, v22, v21, 16
	v_alignbit_b32 v22, v23, v22, 16
	v_alignbit_b32 v23, v24, v23, 16
	v_alignbit_b32 v24, v25, v24, 16
	v_alignbit_b32 v25, v26, v25, 16
	v_alignbit_b32 v26, v27, v26, 16
	v_alignbit_b32 v27, v28, v27, 16
	v_alignbit_b32 v28, v29, v28, 16
	v_alignbit_b32 v29, v42, v29, 16
	v_fma_mixhi_f16 v31, v57, v52, 0
	v_cvt_scalef32_pk32_fp6_f16 v[42:47], v[16:31], 1.0
	s_mov_b32 s48, 0x55555555
	s_mov_b32 s49, 0x55555555
	s_mov_b64 s[50:51], exec
	v_lshl_add_u64 v[16:17], s[14:15], 0, v[32:33]
	s_and_b64 exec, s[50:51], s[48:49]
	global_store_dwordx4 v[16:17], v[42:45], off
	s_andn2_b64 exec, s[50:51], s[48:49]
	global_store_dwordx4 v[16:17], v[44:47], off
	s_mov_b64 exec, s[50:51]
	v_lshl_add_u64 v[16:17], s[14:15], 0, v[34:35]
	s_and_b64 exec, s[50:51], s[48:49]
	global_store_dwordx2 v[16:17], v[46:47], off
	s_andn2_b64 exec, s[50:51], s[48:49]
	global_store_dwordx2 v[16:17], v[42:43], off
	s_mov_b64 exec, s[50:51]
	s_and_saveexec_b64 s[8:9], s[4:5]
	s_cbranch_execz .LBB0_132
	s_and_b64 s[6:7], s[6:7], exec
	s_cselect_b32 s7, s59, s57
	s_cselect_b32 s6, s58, s56
	s_lshl_b32 s12, s12, 2
	v_mul_f32_e32 v16, 0x3e124925, v41
	v_cndmask_b32_e32 v16, 1.0, v16, vcc
	v_mov_b32_e32 v17, s12
	global_store_dword v17, v16, s[6:7]
	s_branch .LBB0_132

.LBB0_145:
	v_mov_b32_e32 v0, v186
	v_readlane_b32 s4, v242, 0
	v_ashrrev_i32_e32 v1, 6, v0
	s_nop 0
	v_add_u32_e32 v1, s4, v1
	s_nop 0
	v_readfirstlane_b32 s10, v1
	s_cmpk_gt_i32 s10, 0x7fff
	s_cbranch_scc1 .LBB0_150
	s_load_dword s4, s[80:81], 0x10
	v_and_b32_e32 v1, 63, v0
	v_and_b32_e32 v2, 64, v179
	v_lshlrev_b32_e32 v0, 2, v1
	v_add_u32_e32 v2, 64, v2
	s_waitcnt lgkmcnt(0)
	s_lshr_b32 s4, s4, 16
	s_cmp_lg_u32 s4, 0
	s_cselect_b64 s[4:5], -1, 0
	s_cmp_lg_u64 s[4:5], 0
	s_addc_u32 s4, s78, 0
	s_lshl_b32 s11, s4, 3
	v_lshrrev_b32_e32 v16, 3, v1
	v_mul_u32_u24_e32 v16, 3, v16
	v_lshlrev_b32_e32 v16, 20, v16
	v_bfe_u32 v18, v1, 1, 2
	v_lshl_add_u32 v16, v18, 4, v16
	v_and_b32_e32 v3, 1, v1
	v_lshl_add_u32 v18, v3, 3, v16
	v_add_u32_e32 v18, 64, v18
	v_lshl_add_u32 v16, v3, 7, v16
	v_cmp_eq_u32_e64 s[4:5], 0, v1
	v_xor_b32_e32 v1, 1, v179
	v_cmp_lt_i32_e32 vcc, v1, v2
	v_mov_b32_e32 v17, 0
	v_mov_b32_e32 v19, v17
	v_cndmask_b32_e32 v1, v179, v1, vcc
	v_lshlrev_b32_e32 v22, 2, v1
	v_xor_b32_e32 v1, 2, v179
	v_cmp_lt_i32_e32 vcc, v1, v2
	v_lshlrev_b32_e32 v20, 2, v0
	v_mov_b32_e32 v21, v17
	v_cndmask_b32_e32 v1, v179, v1, vcc
	v_lshlrev_b32_e32 v23, 2, v1
	v_xor_b32_e32 v1, 4, v179
	v_cmp_lt_i32_e32 vcc, v1, v2
	s_movk_i32 s12, 0x1000
	s_mov_b32 s13, 0x40e00000
	v_cndmask_b32_e32 v1, v179, v1, vcc
	v_lshlrev_b32_e32 v24, 2, v1
	v_xor_b32_e32 v1, 8, v179
	v_cmp_lt_i32_e32 vcc, v1, v2
	s_nop 1
	v_cndmask_b32_e32 v1, v179, v1, vcc
	v_lshlrev_b32_e32 v25, 2, v1
	v_xor_b32_e32 v1, 16, v179
	v_cmp_lt_i32_e32 vcc, v1, v2
	s_nop 1
	v_cndmask_b32_e32 v1, v179, v1, vcc
	v_lshlrev_b32_e32 v26, 2, v1
	v_xor_b32_e32 v1, 32, v179
	v_cmp_lt_i32_e32 vcc, v1, v2
	s_nop 1
	v_cndmask_b32_e32 v1, v179, v1, vcc
	v_lshlrev_b32_e32 v27, 2, v1
	s_branch .LBB0_148

.LBB0_148:
	s_and_b32 s14, s10, 0x3fff
	s_lshl_b32 s15, s14, 13
	s_cmpk_gt_i32 s10, 0x3fff
	s_cselect_b64 s[6:7], -1, 0
	s_and_b64 s[8:9], s[6:7], exec
	s_cselect_b32 s16, s66, s64
	s_cselect_b32 s17, s67, s65
	s_cselect_b32 s8, s71, s69
	s_cselect_b32 s9, s70, s68
	s_add_u32 s16, s16, s15
	s_addc_u32 s17, s17, 0
	v_lshl_add_u64 v[28:29], s[16:17], 0, v[20:21]
	global_load_dwordx4 v[0:3], v20, s[16:17]
	global_load_dwordx4 v[4:7], v20, s[16:17] offset:1024
	global_load_dwordx4 v[8:11], v20, s[16:17] offset:2048
	global_load_dwordx4 v[12:15], v20, s[16:17] offset:3072
	v_add_co_u32_e32 v44, vcc, s12, v28
	s_mul_i32 s15, s14, 0xc0
	s_nop 0
	v_addc_co_u32_e32 v45, vcc, 0, v29, vcc
	global_load_dwordx4 v[28:31], v[44:45], off
	global_load_dwordx4 v[32:35], v[44:45], off offset:1024
	global_load_dwordx4 v[36:39], v[44:45], off offset:2048
	global_load_dwordx4 v[40:43], v[44:45], off offset:3072
	s_waitcnt vmcnt(7)
	v_max_f32_e64 v44, |v3|, |v3|
	v_max_f32_e64 v45, |v2|, |v2|
	s_waitcnt vmcnt(6)
	v_max_f32_e64 v46, |v7|, |v7|
	v_max_f32_e64 v47, |v6|, |v6|
	s_waitcnt vmcnt(5)
	v_max_f32_e64 v48, |v11|, |v11|
	v_max_f32_e64 v49, |v10|, |v10|
	s_waitcnt vmcnt(4)
	v_max_f32_e64 v50, |v15|, |v15|
	v_max_f32_e64 v51, |v14|, |v14|
	v_max_f32_e32 v44, v45, v44
	v_max_f32_e32 v45, v47, v46
	v_max_f32_e32 v46, v49, v48
	v_max_f32_e32 v47, v51, v50
	v_max3_f32 v44, |v0|, |v1|, v44
	v_max3_f32 v45, |v4|, |v5|, v45
	s_waitcnt vmcnt(3)
	v_max_f32_e64 v48, |v31|, |v31|
	v_max_f32_e64 v49, |v30|, |v30|
	s_waitcnt vmcnt(2)
	v_max_f32_e64 v50, |v35|, |v35|
	v_max_f32_e64 v51, |v34|, |v34|
	v_max3_f32 v46, |v8|, |v9|, v46
	v_max3_f32 v47, |v12|, |v13|, v47
	s_waitcnt vmcnt(1)
	v_max_f32_e64 v52, |v39|, |v39|
	v_max_f32_e64 v53, |v38|, |v38|
	s_waitcnt vmcnt(0)
	v_max_f32_e64 v54, |v43|, |v43|
	v_max_f32_e64 v55, |v42|, |v42|
	v_max3_f32 v44, v44, 0, v45
	v_max_f32_e32 v45, v49, v48
	v_max_f32_e32 v48, v51, v50
	v_max_f32_e32 v49, v53, v52
	v_max_f32_e32 v50, v55, v54
	v_max3_f32 v44, v44, v46, v47
	v_max3_f32 v45, |v28|, |v29|, v45
	v_max3_f32 v46, |v32|, |v33|, v48
	v_max3_f32 v47, |v36|, |v37|, v49
	v_max3_f32 v48, |v40|, |v41|, v50
	v_max3_f32 v44, v44, v45, v46
	v_max3_f32 v44, v44, v47, v48
	ds_bpermute_b32 v45, v22, v44
	s_waitcnt lgkmcnt(0)
	v_max_f32_e32 v45, v45, v45
	v_max_f32_e32 v46, v44, v45
	ds_bpermute_b32 v47, v23, v46
	v_mov_b32_e32 v44, v1
	v_mov_b32_e32 v45, v2
	v_pk_mov_b32 v[2:3], v[2:3], v[4:5] op_sel:[1,0]
	v_mov_b32_e32 v4, v5
	s_waitcnt lgkmcnt(0)
	v_max_f32_e32 v1, v47, v47
	v_max_f32_e32 v1, v46, v1
	ds_bpermute_b32 v46, v24, v1
	v_mov_b32_e32 v5, v6
	v_pk_mov_b32 v[6:7], v[6:7], v[8:9] op_sel:[1,0]
	v_mov_b32_e32 v8, v9
	v_mov_b32_e32 v47, v30
	s_waitcnt lgkmcnt(0)
	v_max_f32_e32 v9, v46, v46
	v_max_f32_e32 v1, v1, v9
	ds_bpermute_b32 v46, v25, v1
	v_mov_b32_e32 v9, v10
	v_pk_mov_b32 v[10:11], v[10:11], v[12:13] op_sel:[1,0]
	v_mov_b32_e32 v12, v13
	v_mov_b32_e32 v13, v14
	s_waitcnt lgkmcnt(0)
	v_max_f32_e32 v14, v46, v46
	v_max_f32_e32 v1, v1, v14
	ds_bpermute_b32 v48, v26, v1
	v_pk_mov_b32 v[14:15], v[14:15], v[28:29] op_sel:[1,0]
	v_mov_b32_e32 v46, v29
	v_pk_mov_b32 v[30:31], v[30:31], v[32:33] op_sel:[1,0]
	v_mov_b32_e32 v32, v33
	s_waitcnt lgkmcnt(0)
	v_max_f32_e32 v28, v48, v48
	v_max_f32_e32 v1, v1, v28
	ds_bpermute_b32 v28, v27, v1
	v_mov_b32_e32 v33, v34
	v_pk_mov_b32 v[34:35], v[34:35], v[36:37] op_sel:[1,0]
	v_mov_b32_e32 v36, v37
	v_mov_b32_e32 v37, v38
	s_waitcnt lgkmcnt(0)
	v_max_f32_e32 v28, v28, v28
	v_max_f32_e32 v28, v1, v28
	v_div_scale_f32 v1, s[16:17], v28, v28, s13
	v_rcp_f32_e32 v29, v1
	v_div_scale_f32 v48, vcc, s13, v28, s13
	s_add_u32 s16, s9, s15
	v_fma_f32 v49, -v1, v29, 1.0
	v_fmac_f32_e32 v29, v49, v29
	v_mul_f32_e32 v49, v48, v29
	v_fma_f32 v50, -v1, v49, v48
	v_fmac_f32_e32 v49, v50, v29
	v_fma_f32 v1, -v1, v49, v48
	v_div_fmas_f32 v1, v1, v29, v49
	v_div_fixup_f32 v1, v1, v28, s13
	v_cmp_lt_f32_e32 vcc, 0, v28
	s_addc_u32 s17, s8, 0
	s_nop 0
	v_cndmask_b32_e32 v48, 1.0, v1, vcc
	v_pk_mul_f32 v[2:3], v[2:3], v[48:49] op_sel_hi:[1,0]
	v_pk_mul_f32 v[4:5], v[4:5], v[48:49] op_sel_hi:[1,0]
	v_pk_mul_f32 v[8:9], v[8:9], v[48:49] op_sel_hi:[1,0]
	v_pk_mul_f32 v[14:15], v[14:15], v[48:49] op_sel_hi:[1,0]
	v_fma_mixlo_f16 v29, v0, v48, 0
	v_pk_mul_f32 v[0:1], v[44:45], v[48:49] op_sel_hi:[1,0]
	v_cvt_pk_f16_f32 v2, v2, v3
	v_cvt_pk_f16_f32 v3, v4, v5
	v_cvt_pk_f16_f32 v5, v8, v9
	v_cvt_pk_f16_f32 v8, v14, v15
	v_pk_mov_b32 v[14:15], v[38:39], v[40:41] op_sel:[1,0]
	v_cvt_pk_f16_f32 v1, v0, v1
	v_pk_mul_f32 v[14:15], v[14:15], v[48:49] op_sel_hi:[1,0]
	v_pack_b32_f16 v0, v29, v1
	v_cvt_pk_f16_f32 v29, v14, v15
	v_mov_b32_e32 v14, v41
	v_mov_b32_e32 v15, v42
	v_pk_mul_f32 v[14:15], v[14:15], v[48:49] op_sel_hi:[1,0]
	v_pk_mul_f32 v[6:7], v[6:7], v[48:49] op_sel_hi:[1,0]
	v_pk_mul_f32 v[10:11], v[10:11], v[48:49] op_sel_hi:[1,0]
	v_pk_mul_f32 v[12:13], v[12:13], v[48:49] op_sel_hi:[1,0]
	v_pk_mul_f32 v[44:45], v[46:47], v[48:49] op_sel_hi:[1,0]
	v_pk_mul_f32 v[30:31], v[30:31], v[48:49] op_sel_hi:[1,0]
	v_pk_mul_f32 v[32:33], v[32:33], v[48:49] op_sel_hi:[1,0]
	v_pk_mul_f32 v[34:35], v[34:35], v[48:49] op_sel_hi:[1,0]
	v_pk_mul_f32 v[36:37], v[36:37], v[48:49] op_sel_hi:[1,0]
	v_cvt_pk_f16_f32 v15, v14, v15
	v_cvt_pk_f16_f32 v4, v6, v7
	v_cvt_pk_f16_f32 v6, v10, v11
	v_cvt_pk_f16_f32 v7, v12, v13
	v_cvt_pk_f16_f32 v9, v44, v45
	v_cvt_pk_f16_f32 v10, v30, v31
	v_cvt_pk_f16_f32 v11, v32, v33
	v_cvt_pk_f16_f32 v12, v34, v35
	v_cvt_pk_f16_f32 v13, v36, v37
	v_alignbit_b32 v14, v15, v29, 16
	v_lshrrev_b32_e32 v15, 16, v15
	v_alignbit_b32 v1, v2, v1, 16
	v_alignbit_b32 v2, v3, v2, 16
	v_alignbit_b32 v3, v4, v3, 16
	v_alignbit_b32 v4, v5, v4, 16
	v_alignbit_b32 v5, v6, v5, 16
	v_alignbit_b32 v6, v7, v6, 16
	v_alignbit_b32 v7, v8, v7, 16
	v_alignbit_b32 v8, v9, v8, 16
	v_alignbit_b32 v9, v10, v9, 16
	v_alignbit_b32 v10, v11, v10, 16
	v_alignbit_b32 v11, v12, v11, 16
	v_alignbit_b32 v12, v13, v12, 16
	v_alignbit_b32 v13, v29, v13, 16
	v_fma_mixhi_f16 v15, v43, v48, 0
	v_cvt_scalef32_pk32_fp6_f16 v[30:35], v[0:15], 1.0
	s_mov_b32 s48, 0x55555555
	s_mov_b32 s49, 0x55555555
	s_mov_b64 s[50:51], exec
	v_lshl_add_u64 v[0:1], s[16:17], 0, v[16:17]
	s_and_b64 exec, s[50:51], s[48:49]
	global_store_dwordx4 v[0:1], v[30:33], off
	s_andn2_b64 exec, s[50:51], s[48:49]
	global_store_dwordx4 v[0:1], v[32:35], off
	s_mov_b64 exec, s[50:51]
	v_lshl_add_u64 v[0:1], s[16:17], 0, v[18:19]
	s_and_b64 exec, s[50:51], s[48:49]
	global_store_dwordx2 v[0:1], v[34:35], off
	s_andn2_b64 exec, s[50:51], s[48:49]
	global_store_dwordx2 v[0:1], v[30:31], off
	s_mov_b64 exec, s[50:51]
	s_and_saveexec_b64 s[8:9], s[4:5]
	s_cbranch_execz .LBB0_147
	s_and_b64 s[6:7], s[6:7], exec
	s_cselect_b32 s7, s59, s57
	s_cselect_b32 s6, s58, s56
	s_lshl_b32 s14, s14, 2
	v_mul_f32_e32 v0, 0x3e124925, v28
	v_cndmask_b32_e32 v0, 1.0, v0, vcc
	v_mov_b32_e32 v1, s14
	global_store_dword v1, v0, s[6:7]
	s_branch .LBB0_147

.LBB0_217:
	s_or_b64 exec, exec, s[4:5]
	s_barrier
	v_readlane_b32 s2, v242, 0
	v_ashrrev_i32_e32 v0, 6, v186
	s_nop 0
	v_add_u32_e32 v0, s2, v0
	s_nop 0
	v_readfirstlane_b32 s4, v0
	s_mov_b32 s5, s76
	s_cmpk_gt_i32 s4, 0x3fff
	s_cbranch_scc1 .LBB0_226
	s_load_dwordx2 s[28:29], s[0:1], 0xb0
	s_load_dwordx2 s[26:27], s[0:1], 0xc0
	s_load_dwordx4 s[16:19], s[0:1], 0xf0
	s_load_dwordx2 s[10:11], s[0:1], 0x100
	s_load_dwordx4 s[20:23], s[0:1], 0x108
	s_load_dwordx4 s[12:15], s[0:1], 0x148
	s_load_dwordx2 s[24:25], s[0:1], 0x158
	v_lshrrev_b32_e32 v239, 6, v186
	v_and_b32_e32 v251, 63, v186
	v_readfirstlane_b32 s64, v239
	s_lshl_b32 s64, s64, 13
	s_add_i32 s64, s64, 16
	v_and_b32_e32 v236, 3, v251
	v_lshrrev_b32_e32 v237, 2, v251
	v_lshlrev_b32_e32 v244, 4, v236
	v_mov_b32_e32 v247, v244
	v_lshl_add_u32 v245, v251, 3, s64
	v_lshl_add_u32 v246, v237, 5, s64
	v_add_u32_e32 v255, 0x1000, v246
	v_lshlrev_b32_e32 v238, 7, v236
	v_lshl_add_u32 v252, v237, 2, v238
	v_and_b32_e32 v238, 15, v251
	v_lshrrev_b32_e32 v239, 4, v251
	v_lshl_add_u32 v238, v238, 3, v239
	v_lshl_add_u32 v253, v238, 2, s64
	v_bfe_u32 v238, v251, 3, 1
	v_bfe_u32 v239, v251, 2, 1
	v_bfe_u32 v240, v251, 4, 1
	v_bfe_u32 v241, v251, 5, 1
	v_lshl_add_u32 v239, v239, 1, v240
	v_lshl_add_u32 v239, v239, 1, v241
	v_lshlrev_b32_e32 v240, 3, v238
	v_lshl_add_u32 v240, v236, 4, v240
	v_lshl_add_u32 v248, v239, 9, v240
	v_lshlrev_b32_e32 v240, 4, v238
	v_lshl_add_u32 v240, v236, 5, v240
	v_lshl_add_u32 v249, v239, 10, v240
	v_xor_b32_e32 v250, 32, v251
	v_lshlrev_b32_e32 v250, 2, v250
	v_mov_b32_e32 v254, 0
	s_mov_b32 s40, 0xaaaaaaaa
	s_mov_b32 s41, 0xaaaaaaaa
	s_mov_b32 s42, 0xcccccccc
	s_mov_b32 s43, 0xcccccccc
	s_mov_b32 s44, 0xf0f0f0f0
	s_mov_b32 s45, 0xf0f0f0f0
	s_mov_b32 s46, 0xff00ff00
	s_mov_b32 s47, 0xff00ff00
	s_mov_b32 s48, 0xffff0000
	s_mov_b32 s49, 0xffff0000
	s_mov_b32 s50, 0
	s_mov_b32 s51, -1
	s_movk_i32 s52, 0xc0
	s_mov_b32 s66, 0x378e98ab
	s_mov_b32 s67, 0xb9c68948
	s_mov_b32 s68, 0x3b7cd369
	s_mov_b32 s69, 0xbcc618b2
	s_mov_b32 s70, 0x3dda74e4
	s_mov_b32 s71, 0x3f228afd
	s_mov_b32 s72, 0x3e03c728
	s_mov_b32 s73, 0xbfb8aa3b
	s_mov_b32 s74, 0x42ce8ed0
	s_mov_b32 s75, 0xc2b17218
	s_mov_b32 s76, 0x3ba10414
	s_mov_b32 s77, 0x7fffffff
	s_mov_b32 s6, s4
	s_waitcnt lgkmcnt(0)
.Lex_chunk:
	s_movk_i32 s36, 0
	s_mul_i32 s37, s36, s5
	s_add_i32 s37, s37, s6
	s_min_u32 s37, s37, 0x3fff
	s_lshl_b32 s37, s37, 9
	s_add_u32 s82, s12, s37
	s_addc_u32 s83, s13, 0
	v_lshlrev_b32_e32 v243, 2, v251
	global_load_dword v140, v243, s[82:83]
	global_load_dword v141, v243, s[82:83] offset:256
	s_movk_i32 s36, 1
	s_mul_i32 s37, s36, s5
	s_add_i32 s37, s37, s6
	s_min_u32 s37, s37, 0x3fff
	s_lshl_b32 s37, s37, 9
	s_add_u32 s82, s12, s37
	s_addc_u32 s83, s13, 0
	v_lshlrev_b32_e32 v243, 2, v251
	global_load_dword v142, v243, s[82:83]
	global_load_dword v143, v243, s[82:83] offset:256
	s_movk_i32 s36, 2
	s_mul_i32 s37, s36, s5
	s_add_i32 s37, s37, s6
	s_min_u32 s37, s37, 0x3fff
	s_lshl_b32 s37, s37, 9
	s_add_u32 s82, s12, s37
	s_addc_u32 s83, s13, 0
	v_lshlrev_b32_e32 v243, 2, v251
	global_load_dword v144, v243, s[82:83]
	global_load_dword v145, v243, s[82:83] offset:256
	s_movk_i32 s36, 3
	s_mul_i32 s37, s36, s5
	s_add_i32 s37, s37, s6
	s_min_u32 s37, s37, 0x3fff
	s_lshl_b32 s37, s37, 9
	s_add_u32 s82, s12, s37
	s_addc_u32 s83, s13, 0
	v_lshlrev_b32_e32 v243, 2, v251
	global_load_dword v146, v243, s[82:83]
	global_load_dword v147, v243, s[82:83] offset:256
	s_movk_i32 s36, 4
	s_mul_i32 s37, s36, s5
	s_add_i32 s37, s37, s6
	s_min_u32 s37, s37, 0x3fff
	s_lshl_b32 s37, s37, 9
	s_add_u32 s82, s12, s37
	s_addc_u32 s83, s13, 0
	v_lshlrev_b32_e32 v243, 2, v251
	global_load_dword v148, v243, s[82:83]
	global_load_dword v149, v243, s[82:83] offset:256
	s_movk_i32 s36, 5
	s_mul_i32 s37, s36, s5
	s_add_i32 s37, s37, s6
	s_min_u32 s37, s37, 0x3fff
	s_lshl_b32 s37, s37, 9
	s_add_u32 s82, s12, s37
	s_addc_u32 s83, s13, 0
	v_lshlrev_b32_e32 v243, 2, v251
	global_load_dword v150, v243, s[82:83]
	global_load_dword v151, v243, s[82:83] offset:256
	s_movk_i32 s36, 6
	s_mul_i32 s37, s36, s5
	s_add_i32 s37, s37, s6
	s_min_u32 s37, s37, 0x3fff
	s_lshl_b32 s37, s37, 9
	s_add_u32 s82, s12, s37
	s_addc_u32 s83, s13, 0
	v_lshlrev_b32_e32 v243, 2, v251
	global_load_dword v152, v243, s[82:83]
	global_load_dword v153, v243, s[82:83] offset:256
	s_movk_i32 s36, 7
	s_mul_i32 s37, s36, s5
	s_add_i32 s37, s37, s6
	s_min_u32 s37, s37, 0x3fff
	s_lshl_b32 s37, s37, 9
	s_add_u32 s82, s12, s37
	s_addc_u32 s83, s13, 0
	v_lshlrev_b32_e32 v243, 2, v251
	global_load_dword v154, v243, s[82:83]
	global_load_dword v155, v243, s[82:83] offset:256
	s_waitcnt vmcnt(0)
	ds_write_b32 v253, v140 offset:0
	ds_write_b32 v253, v141 offset:16
	ds_write_b32 v253, v142 offset:512
	ds_write_b32 v253, v143 offset:528
	ds_write_b32 v253, v144 offset:1024
	ds_write_b32 v253, v145 offset:1040
	ds_write_b32 v253, v146 offset:1536
	ds_write_b32 v253, v147 offset:1552
	ds_write_b32 v253, v148 offset:2048
	ds_write_b32 v253, v149 offset:2064
	ds_write_b32 v253, v150 offset:2560
	ds_write_b32 v253, v151 offset:2576
	ds_write_b32 v253, v152 offset:3072
	ds_write_b32 v253, v153 offset:3088
	ds_write_b32 v253, v154 offset:3584
	ds_write_b32 v253, v155 offset:3600
	s_waitcnt lgkmcnt(0)
	s_mov_b32 s8, 0
	s_mov_b32 s7, 0
	s_mov_b32 s54, 0
	s_mov_b32 s53, 0
	s_mul_i32 s55, s53, s5
	s_add_i32 s55, s55, s6
	s_min_u32 s55, s55, 0x3fff
	s_and_b32 s34, s54, 7
	s_mul_i32 s34, s34, 0x300000
	s_cmp_lt_u32 s54, 8
	s_cselect_b32 s30, s16, s18
	s_cselect_b32 s31, s17, s19
	s_add_u32 s30, s30, s34
	s_addc_u32 s31, s31, 0
	s_and_b32 s34, s54, 7
	s_lshl_b32 s34, s34, 6
	s_lshl_b32 s35, s55, 12
	s_add_u32 s34, s34, s35
	s_add_u32 s32, s10, s34
	s_addc_u32 s33, s11, 0
	s_lshl_b32 s34, s53, 9
	v_add_u32_e32 v240, s34, v246
	ds_read_b128 v[132:135], v240
	ds_read_b128 v[136:139], v240 offset:16
	s_waitcnt lgkmcnt(0)
	global_load_dwordx4 v[64:67], v247, s[32:33]
	global_load_dwordx4 v[68:71], v247, s[32:33] offset:512
	global_load_dwordx4 v[72:75], v247, s[32:33] offset:1024
	global_load_dwordx4 v[76:79], v247, s[32:33] offset:1536
	global_load_dwordx4 v[80:83], v247, s[32:33] offset:2048
	global_load_dwordx4 v[84:87], v247, s[32:33] offset:2560
	global_load_dwordx4 v[88:91], v247, s[32:33] offset:3072
	global_load_dwordx4 v[92:95], v247, s[32:33] offset:3584
	v_mad_u32_u24 v241, v132, s52, v244
	global_load_dwordx4 v[140:143], v241, s[30:31]
	global_load_dwordx4 v[144:147], v241, s[30:31] offset:64
	global_load_dwordx4 v[148:151], v241, s[30:31] offset:128
	v_mad_u32_u24 v241, v133, s52, v244
	global_load_dwordx4 v[152:155], v241, s[30:31]
	global_load_dwordx4 v[156:159], v241, s[30:31] offset:64
	global_load_dwordx4 v[160:163], v241, s[30:31] offset:128
	v_mad_u32_u24 v241, v134, s52, v244
	global_load_dwordx4 v[164:167], v241, s[30:31]
	global_load_dwordx4 v[168:171], v241, s[30:31] offset:64
	global_load_dwordx4 v[172:175], v241, s[30:31] offset:128
	v_mad_u32_u24 v241, v135, s52, v244
	global_load_dwordx4 v[176:179], v241, s[30:31]
	global_load_dwordx4 v[180:183], v241, s[30:31] offset:64
	global_load_dwordx4 v[184:187], v241, s[30:31] offset:128
	v_mad_u32_u24 v241, v136, s52, v244
	global_load_dwordx4 v[188:191], v241, s[30:31]
	global_load_dwordx4 v[192:195], v241, s[30:31] offset:64
	global_load_dwordx4 v[196:199], v241, s[30:31] offset:128
	v_mad_u32_u24 v241, v137, s52, v244
	global_load_dwordx4 v[200:203], v241, s[30:31]
	global_load_dwordx4 v[204:207], v241, s[30:31] offset:64
	global_load_dwordx4 v[208:211], v241, s[30:31] offset:128
	v_mad_u32_u24 v241, v138, s52, v244
	global_load_dwordx4 v[212:215], v241, s[30:31]
	global_load_dwordx4 v[216:219], v241, s[30:31] offset:64
	global_load_dwordx4 v[220:223], v241, s[30:31] offset:128
	v_mad_u32_u24 v241, v139, s52, v244
	global_load_dwordx4 v[224:227], v241, s[30:31]
	global_load_dwordx4 v[228:231], v241, s[30:31] offset:64
	global_load_dwordx4 v[232:235], v241, s[30:31] offset:128
	s_add_i32 s53, s7, 1
	s_mov_b32 s54, s8
	s_cmp_eq_u32 s53, 8
	s_cselect_b32 s53, 0, s53
	s_cselect_b32 s34, 1, 0
	s_add_i32 s54, s54, s34
	s_mul_i32 s55, s53, s5
	s_add_i32 s55, s55, s6
	s_min_u32 s55, s55, 0x3fff
	s_and_b32 s34, s54, 7
	s_mul_i32 s34, s34, 0x300000
	s_cmp_lt_u32 s54, 8
	s_cselect_b32 s30, s16, s18
	s_cselect_b32 s31, s17, s19
	s_add_u32 s30, s30, s34
	s_addc_u32 s31, s31, 0
	s_and_b32 s34, s54, 7
	s_lshl_b32 s34, s34, 6
	s_lshl_b32 s35, s55, 12
	s_add_u32 s34, s34, s35
	s_add_u32 s32, s10, s34
	s_addc_u32 s33, s11, 0
	s_lshl_b32 s34, s53, 9
	v_add_u32_e32 v240, s34, v246
	ds_read_b128 v[132:135], v240
	ds_read_b128 v[136:139], v240 offset:16
.Lex_uloop:
	s_waitcnt vmcnt(24)
	v_mov_b64_e32 v[32:33], v[64:65]
	v_mov_b64_e32 v[34:35], v[66:67]
	v_mov_b64_e32 v[36:37], v[68:69]
	v_mov_b64_e32 v[38:39], v[70:71]
	v_mov_b64_e32 v[40:41], v[72:73]
	v_mov_b64_e32 v[42:43], v[74:75]
	v_mov_b64_e32 v[44:45], v[76:77]
	v_mov_b64_e32 v[46:47], v[78:79]
	v_mov_b64_e32 v[48:49], v[80:81]
	v_mov_b64_e32 v[50:51], v[82:83]
	v_mov_b64_e32 v[52:53], v[84:85]
	v_mov_b64_e32 v[54:55], v[86:87]
	v_mov_b64_e32 v[56:57], v[88:89]
	v_mov_b64_e32 v[58:59], v[90:91]
	v_mov_b64_e32 v[60:61], v[92:93]
	v_mov_b64_e32 v[62:63], v[94:95]
	s_waitcnt lgkmcnt(0)
	s_waitcnt vmcnt(21)
	v_cvt_scalef32_pk32_bf16_fp6 v[0:15], v[140:145], 1.0
	v_dot2_f32_bf16 v16, v0, v32, 0
	v_dot2_f32_bf16 v17, v1, v33, 0
	v_dot2_f32_bf16 v16, v2, v36, v16
	v_dot2_f32_bf16 v17, v3, v37, v17
	v_dot2_f32_bf16 v16, v4, v40, v16
	v_dot2_f32_bf16 v17, v5, v41, v17
	v_dot2_f32_bf16 v16, v6, v44, v16
	v_dot2_f32_bf16 v17, v7, v45, v17
	v_dot2_f32_bf16 v16, v8, v48, v16
	v_dot2_f32_bf16 v17, v9, v49, v17
	v_dot2_f32_bf16 v16, v10, v52, v16
	v_dot2_f32_bf16 v17, v11, v53, v17
	v_dot2_f32_bf16 v16, v12, v56, v16
	v_dot2_f32_bf16 v17, v13, v57, v17
	v_dot2_f32_bf16 v16, v14, v60, v16
	v_dot2_f32_bf16 v17, v15, v61, v17
	v_cvt_scalef32_pk32_bf16_fp6 v[0:15], v[146:151], 1.0
	v_dot2_f32_bf16 v16, v0, v34, v16
	v_dot2_f32_bf16 v17, v1, v35, v17
	v_dot2_f32_bf16 v16, v2, v38, v16
	v_dot2_f32_bf16 v17, v3, v39, v17
	v_dot2_f32_bf16 v16, v4, v42, v16
	v_dot2_f32_bf16 v17, v5, v43, v17
	v_dot2_f32_bf16 v16, v6, v46, v16
	v_dot2_f32_bf16 v17, v7, v47, v17
	v_dot2_f32_bf16 v16, v8, v50, v16
	v_dot2_f32_bf16 v17, v9, v51, v17
	v_dot2_f32_bf16 v16, v10, v54, v16
	v_dot2_f32_bf16 v17, v11, v55, v17
	v_dot2_f32_bf16 v16, v12, v58, v16
	v_dot2_f32_bf16 v17, v13, v59, v17
	v_dot2_f32_bf16 v16, v14, v62, v16
	v_dot2_f32_bf16 v17, v15, v63, v17
	s_nop 2
	v_add_f32_e32 v124, v16, v17
	global_load_dwordx4 v[64:67], v247, s[32:33]
	global_load_dwordx4 v[68:71], v247, s[32:33] offset:512
	global_load_dwordx4 v[72:75], v247, s[32:33] offset:1024
	global_load_dwordx4 v[76:79], v247, s[32:33] offset:1536
	global_load_dwordx4 v[80:83], v247, s[32:33] offset:2048
	global_load_dwordx4 v[84:87], v247, s[32:33] offset:2560
	global_load_dwordx4 v[88:91], v247, s[32:33] offset:3072
	global_load_dwordx4 v[92:95], v247, s[32:33] offset:3584
	v_mad_u32_u24 v241, v132, s52, v244
	global_load_dwordx4 v[140:143], v241, s[30:31]
	global_load_dwordx4 v[144:147], v241, s[30:31] offset:64
	global_load_dwordx4 v[148:151], v241, s[30:31] offset:128
	s_waitcnt vmcnt(29)
	v_cvt_scalef32_pk32_bf16_fp6 v[0:15], v[152:157], 1.0
	v_dot2_f32_bf16 v16, v0, v32, 0
	v_dot2_f32_bf16 v17, v1, v33, 0
	v_dot2_f32_bf16 v16, v2, v36, v16
	v_dot2_f32_bf16 v17, v3, v37, v17
	v_dot2_f32_bf16 v16, v4, v40, v16
	v_dot2_f32_bf16 v17, v5, v41, v17
	v_dot2_f32_bf16 v16, v6, v44, v16
	v_dot2_f32_bf16 v17, v7, v45, v17
	v_dot2_f32_bf16 v16, v8, v48, v16
	v_dot2_f32_bf16 v17, v9, v49, v17
	v_dot2_f32_bf16 v16, v10, v52, v16
	v_dot2_f32_bf16 v17, v11, v53, v17
	v_dot2_f32_bf16 v16, v12, v56, v16
	v_dot2_f32_bf16 v17, v13, v57, v17
	v_dot2_f32_bf16 v16, v14, v60, v16
	v_dot2_f32_bf16 v17, v15, v61, v17
	v_cvt_scalef32_pk32_bf16_fp6 v[0:15], v[158:163], 1.0
	v_dot2_f32_bf16 v16, v0, v34, v16
	v_dot2_f32_bf16 v17, v1, v35, v17
	v_dot2_f32_bf16 v16, v2, v38, v16
	v_dot2_f32_bf16 v17, v3, v39, v17
	v_dot2_f32_bf16 v16, v4, v42, v16
	v_dot2_f32_bf16 v17, v5, v43, v17
	v_dot2_f32_bf16 v16, v6, v46, v16
	v_dot2_f32_bf16 v17, v7, v47, v17
	v_dot2_f32_bf16 v16, v8, v50, v16
	v_dot2_f32_bf16 v17, v9, v51, v17
	v_dot2_f32_bf16 v16, v10, v54, v16
	v_dot2_f32_bf16 v17, v11, v55, v17
	v_dot2_f32_bf16 v16, v12, v58, v16
	v_dot2_f32_bf16 v17, v13, v59, v17
	v_dot2_f32_bf16 v16, v14, v62, v16
	v_dot2_f32_bf16 v17, v15, v63, v17
	s_nop 2
	v_add_f32_e32 v125, v16, v17
	v_mad_u32_u24 v241, v133, s52, v244
	global_load_dwordx4 v[152:155], v241, s[30:31]
	global_load_dwordx4 v[156:159], v241, s[30:31] offset:64
	global_load_dwordx4 v[160:163], v241, s[30:31] offset:128
	s_waitcnt vmcnt(29)
	v_cvt_scalef32_pk32_bf16_fp6 v[0:15], v[164:169], 1.0
	v_dot2_f32_bf16 v16, v0, v32, 0
	v_dot2_f32_bf16 v17, v1, v33, 0
	v_dot2_f32_bf16 v16, v2, v36, v16
	v_dot2_f32_bf16 v17, v3, v37, v17
	v_dot2_f32_bf16 v16, v4, v40, v16
	v_dot2_f32_bf16 v17, v5, v41, v17
	v_dot2_f32_bf16 v16, v6, v44, v16
	v_dot2_f32_bf16 v17, v7, v45, v17
	v_dot2_f32_bf16 v16, v8, v48, v16
	v_dot2_f32_bf16 v17, v9, v49, v17
	v_dot2_f32_bf16 v16, v10, v52, v16
	v_dot2_f32_bf16 v17, v11, v53, v17
	v_dot2_f32_bf16 v16, v12, v56, v16
	v_dot2_f32_bf16 v17, v13, v57, v17
	v_dot2_f32_bf16 v16, v14, v60, v16
	v_dot2_f32_bf16 v17, v15, v61, v17
	v_cvt_scalef32_pk32_bf16_fp6 v[0:15], v[170:175], 1.0
	v_dot2_f32_bf16 v16, v0, v34, v16
	v_dot2_f32_bf16 v17, v1, v35, v17
	v_dot2_f32_bf16 v16, v2, v38, v16
	v_dot2_f32_bf16 v17, v3, v39, v17
	v_dot2_f32_bf16 v16, v4, v42, v16
	v_dot2_f32_bf16 v17, v5, v43, v17
	v_dot2_f32_bf16 v16, v6, v46, v16
	v_dot2_f32_bf16 v17, v7, v47, v17
	v_dot2_f32_bf16 v16, v8, v50, v16
	v_dot2_f32_bf16 v17, v9, v51, v17
	v_dot2_f32_bf16 v16, v10, v54, v16
	v_dot2_f32_bf16 v17, v11, v55, v17
	v_dot2_f32_bf16 v16, v12, v58, v16
	v_dot2_f32_bf16 v17, v13, v59, v17
	v_dot2_f32_bf16 v16, v14, v62, v16
	v_dot2_f32_bf16 v17, v15, v63, v17
	s_nop 2
	v_add_f32_e32 v126, v16, v17
	v_mad_u32_u24 v241, v134, s52, v244
	global_load_dwordx4 v[164:167], v241, s[30:31]
	global_load_dwordx4 v[168:171], v241, s[30:31] offset:64
	global_load_dwordx4 v[172:175], v241, s[30:31] offset:128
	s_waitcnt vmcnt(29)
	v_cvt_scalef32_pk32_bf16_fp6 v[0:15], v[176:181], 1.0
	v_dot2_f32_bf16 v16, v0, v32, 0
	v_dot2_f32_bf16 v17, v1, v33, 0
	v_dot2_f32_bf16 v16, v2, v36, v16
	v_dot2_f32_bf16 v17, v3, v37, v17
	v_dot2_f32_bf16 v16, v4, v40, v16
	v_dot2_f32_bf16 v17, v5, v41, v17
	v_dot2_f32_bf16 v16, v6, v44, v16
	v_dot2_f32_bf16 v17, v7, v45, v17
	v_dot2_f32_bf16 v16, v8, v48, v16
	v_dot2_f32_bf16 v17, v9, v49, v17
	v_dot2_f32_bf16 v16, v10, v52, v16
	v_dot2_f32_bf16 v17, v11, v53, v17
	v_dot2_f32_bf16 v16, v12, v56, v16
	v_dot2_f32_bf16 v17, v13, v57, v17
	v_dot2_f32_bf16 v16, v14, v60, v16
	v_dot2_f32_bf16 v17, v15, v61, v17
	v_cvt_scalef32_pk32_bf16_fp6 v[0:15], v[182:187], 1.0
	v_dot2_f32_bf16 v16, v0, v34, v16
	v_dot2_f32_bf16 v17, v1, v35, v17
	v_dot2_f32_bf16 v16, v2, v38, v16
	v_dot2_f32_bf16 v17, v3, v39, v17
	v_dot2_f32_bf16 v16, v4, v42, v16
	v_dot2_f32_bf16 v17, v5, v43, v17
	v_dot2_f32_bf16 v16, v6, v46, v16
	v_dot2_f32_bf16 v17, v7, v47, v17
	v_dot2_f32_bf16 v16, v8, v50, v16
	v_dot2_f32_bf16 v17, v9, v51, v17
	v_dot2_f32_bf16 v16, v10, v54, v16
	v_dot2_f32_bf16 v17, v11, v55, v17
	v_dot2_f32_bf16 v16, v12, v58, v16
	v_dot2_f32_bf16 v17, v13, v59, v17
	v_dot2_f32_bf16 v16, v14, v62, v16
	v_dot2_f32_bf16 v17, v15, v63, v17
	s_nop 2
	v_add_f32_e32 v127, v16, v17
	v_mad_u32_u24 v241, v135, s52, v244
	global_load_dwordx4 v[176:179], v241, s[30:31]
	global_load_dwordx4 v[180:183], v241, s[30:31] offset:64
	global_load_dwordx4 v[184:187], v241, s[30:31] offset:128
	s_waitcnt vmcnt(29)
	v_cvt_scalef32_pk32_bf16_fp6 v[0:15], v[188:193], 1.0
	v_dot2_f32_bf16 v16, v0, v32, 0
	v_dot2_f32_bf16 v17, v1, v33, 0
	v_dot2_f32_bf16 v16, v2, v36, v16
	v_dot2_f32_bf16 v17, v3, v37, v17
	v_dot2_f32_bf16 v16, v4, v40, v16
	v_dot2_f32_bf16 v17, v5, v41, v17
	v_dot2_f32_bf16 v16, v6, v44, v16
	v_dot2_f32_bf16 v17, v7, v45, v17
	v_dot2_f32_bf16 v16, v8, v48, v16
	v_dot2_f32_bf16 v17, v9, v49, v17
	v_dot2_f32_bf16 v16, v10, v52, v16
	v_dot2_f32_bf16 v17, v11, v53, v17
	v_dot2_f32_bf16 v16, v12, v56, v16
	v_dot2_f32_bf16 v17, v13, v57, v17
	v_dot2_f32_bf16 v16, v14, v60, v16
	v_dot2_f32_bf16 v17, v15, v61, v17
	v_cvt_scalef32_pk32_bf16_fp6 v[0:15], v[194:199], 1.0
	v_dot2_f32_bf16 v16, v0, v34, v16
	v_dot2_f32_bf16 v17, v1, v35, v17
	v_dot2_f32_bf16 v16, v2, v38, v16
	v_dot2_f32_bf16 v17, v3, v39, v17
	v_dot2_f32_bf16 v16, v4, v42, v16
	v_dot2_f32_bf16 v17, v5, v43, v17
	v_dot2_f32_bf16 v16, v6, v46, v16
	v_dot2_f32_bf16 v17, v7, v47, v17
	v_dot2_f32_bf16 v16, v8, v50, v16
	v_dot2_f32_bf16 v17, v9, v51, v17
	v_dot2_f32_bf16 v16, v10, v54, v16
	v_dot2_f32_bf16 v17, v11, v55, v17
	v_dot2_f32_bf16 v16, v12, v58, v16
	v_dot2_f32_bf16 v17, v13, v59, v17
	v_dot2_f32_bf16 v16, v14, v62, v16
	v_dot2_f32_bf16 v17, v15, v63, v17
	s_nop 2
	v_add_f32_e32 v128, v16, v17
	v_mad_u32_u24 v241, v136, s52, v244
	global_load_dwordx4 v[188:191], v241, s[30:31]
	global_load_dwordx4 v[192:195], v241, s[30:31] offset:64
	global_load_dwordx4 v[196:199], v241, s[30:31] offset:128
	s_waitcnt vmcnt(29)
	v_cvt_scalef32_pk32_bf16_fp6 v[0:15], v[200:205], 1.0
	v_dot2_f32_bf16 v16, v0, v32, 0
	v_dot2_f32_bf16 v17, v1, v33, 0
	v_dot2_f32_bf16 v16, v2, v36, v16
	v_dot2_f32_bf16 v17, v3, v37, v17
	v_dot2_f32_bf16 v16, v4, v40, v16
	v_dot2_f32_bf16 v17, v5, v41, v17
	v_dot2_f32_bf16 v16, v6, v44, v16
	v_dot2_f32_bf16 v17, v7, v45, v17
	v_dot2_f32_bf16 v16, v8, v48, v16
	v_dot2_f32_bf16 v17, v9, v49, v17
	v_dot2_f32_bf16 v16, v10, v52, v16
	v_dot2_f32_bf16 v17, v11, v53, v17
	v_dot2_f32_bf16 v16, v12, v56, v16
	v_dot2_f32_bf16 v17, v13, v57, v17
	v_dot2_f32_bf16 v16, v14, v60, v16
	v_dot2_f32_bf16 v17, v15, v61, v17
	v_cvt_scalef32_pk32_bf16_fp6 v[0:15], v[206:211], 1.0
	v_dot2_f32_bf16 v16, v0, v34, v16
	v_dot2_f32_bf16 v17, v1, v35, v17
	v_dot2_f32_bf16 v16, v2, v38, v16
	v_dot2_f32_bf16 v17, v3, v39, v17
	v_dot2_f32_bf16 v16, v4, v42, v16
	v_dot2_f32_bf16 v17, v5, v43, v17
	v_dot2_f32_bf16 v16, v6, v46, v16
	v_dot2_f32_bf16 v17, v7, v47, v17
	v_dot2_f32_bf16 v16, v8, v50, v16
	v_dot2_f32_bf16 v17, v9, v51, v17
	v_dot2_f32_bf16 v16, v10, v54, v16
	v_dot2_f32_bf16 v17, v11, v55, v17
	v_dot2_f32_bf16 v16, v12, v58, v16
	v_dot2_f32_bf16 v17, v13, v59, v17
	v_dot2_f32_bf16 v16, v14, v62, v16
	v_dot2_f32_bf16 v17, v15, v63, v17
	s_nop 2
	v_add_f32_e32 v129, v16, v17
	v_mad_u32_u24 v241, v137, s52, v244
	global_load_dwordx4 v[200:203], v241, s[30:31]
	global_load_dwordx4 v[204:207], v241, s[30:31] offset:64
	global_load_dwordx4 v[208:211], v241, s[30:31] offset:128
	s_waitcnt vmcnt(29)
	v_cvt_scalef32_pk32_bf16_fp6 v[0:15], v[212:217], 1.0
	v_dot2_f32_bf16 v16, v0, v32, 0
	v_dot2_f32_bf16 v17, v1, v33, 0
	v_dot2_f32_bf16 v16, v2, v36, v16
	v_dot2_f32_bf16 v17, v3, v37, v17
	v_dot2_f32_bf16 v16, v4, v40, v16
	v_dot2_f32_bf16 v17, v5, v41, v17
	v_dot2_f32_bf16 v16, v6, v44, v16
	v_dot2_f32_bf16 v17, v7, v45, v17
	v_dot2_f32_bf16 v16, v8, v48, v16
	v_dot2_f32_bf16 v17, v9, v49, v17
	v_dot2_f32_bf16 v16, v10, v52, v16
	v_dot2_f32_bf16 v17, v11, v53, v17
	v_dot2_f32_bf16 v16, v12, v56, v16
	v_dot2_f32_bf16 v17, v13, v57, v17
	v_dot2_f32_bf16 v16, v14, v60, v16
	v_dot2_f32_bf16 v17, v15, v61, v17
	v_cvt_scalef32_pk32_bf16_fp6 v[0:15], v[218:223], 1.0
	v_dot2_f32_bf16 v16, v0, v34, v16
	v_dot2_f32_bf16 v17, v1, v35, v17
	v_dot2_f32_bf16 v16, v2, v38, v16
	v_dot2_f32_bf16 v17, v3, v39, v17
	v_dot2_f32_bf16 v16, v4, v42, v16
	v_dot2_f32_bf16 v17, v5, v43, v17
	v_dot2_f32_bf16 v16, v6, v46, v16
	v_dot2_f32_bf16 v17, v7, v47, v17
	v_dot2_f32_bf16 v16, v8, v50, v16
	v_dot2_f32_bf16 v17, v9, v51, v17
	v_dot2_f32_bf16 v16, v10, v54, v16
	v_dot2_f32_bf16 v17, v11, v55, v17
	v_dot2_f32_bf16 v16, v12, v58, v16
	v_dot2_f32_bf16 v17, v13, v59, v17
	v_dot2_f32_bf16 v16, v14, v62, v16
	v_dot2_f32_bf16 v17, v15, v63, v17
	s_nop 2
	v_add_f32_e32 v130, v16, v17
	v_mad_u32_u24 v241, v138, s52, v244
	global_load_dwordx4 v[212:215], v241, s[30:31]
	global_load_dwordx4 v[216:219], v241, s[30:31] offset:64
	global_load_dwordx4 v[220:223], v241, s[30:31] offset:128
	s_waitcnt vmcnt(29)
	v_cvt_scalef32_pk32_bf16_fp6 v[0:15], v[224:229], 1.0
	v_dot2_f32_bf16 v16, v0, v32, 0
	v_dot2_f32_bf16 v17, v1, v33, 0
	v_dot2_f32_bf16 v16, v2, v36, v16
	v_dot2_f32_bf16 v17, v3, v37, v17
	v_dot2_f32_bf16 v16, v4, v40, v16
	v_dot2_f32_bf16 v17, v5, v41, v17
	v_dot2_f32_bf16 v16, v6, v44, v16
	v_dot2_f32_bf16 v17, v7, v45, v17
	v_dot2_f32_bf16 v16, v8, v48, v16
	v_dot2_f32_bf16 v17, v9, v49, v17
	v_dot2_f32_bf16 v16, v10, v52, v16
	v_dot2_f32_bf16 v17, v11, v53, v17
	v_dot2_f32_bf16 v16, v12, v56, v16
	v_dot2_f32_bf16 v17, v13, v57, v17
	v_dot2_f32_bf16 v16, v14, v60, v16
	v_dot2_f32_bf16 v17, v15, v61, v17
	v_cvt_scalef32_pk32_bf16_fp6 v[0:15], v[230:235], 1.0
	v_dot2_f32_bf16 v16, v0, v34, v16
	v_dot2_f32_bf16 v17, v1, v35, v17
	v_dot2_f32_bf16 v16, v2, v38, v16
	v_dot2_f32_bf16 v17, v3, v39, v17
	v_dot2_f32_bf16 v16, v4, v42, v16
	v_dot2_f32_bf16 v17, v5, v43, v17
	v_dot2_f32_bf16 v16, v6, v46, v16
	v_dot2_f32_bf16 v17, v7, v47, v17
	v_dot2_f32_bf16 v16, v8, v50, v16
	v_dot2_f32_bf16 v17, v9, v51, v17
	v_dot2_f32_bf16 v16, v10, v54, v16
	v_dot2_f32_bf16 v17, v11, v55, v17
	v_dot2_f32_bf16 v16, v12, v58, v16
	v_dot2_f32_bf16 v17, v13, v59, v17
	v_dot2_f32_bf16 v16, v14, v62, v16
	v_dot2_f32_bf16 v17, v15, v63, v17
	s_nop 2
	v_add_f32_e32 v131, v16, v17
	v_mad_u32_u24 v241, v139, s52, v244
	global_load_dwordx4 v[224:227], v241, s[30:31]
	global_load_dwordx4 v[228:231], v241, s[30:31] offset:64
	global_load_dwordx4 v[232:235], v241, s[30:31] offset:128
	s_mov_b32 s89, s7
	s_mov_b32 s90, s8
	s_mov_b32 s7, s53
	s_mov_b32 s8, s54
	s_add_i32 s53, s7, 1
	s_mov_b32 s54, s8
	s_cmp_eq_u32 s53, 8
	s_cselect_b32 s53, 0, s53
	s_cselect_b32 s34, 1, 0
	s_add_i32 s54, s54, s34
	s_mul_i32 s55, s53, s5
	s_add_i32 s55, s55, s6
	s_min_u32 s55, s55, 0x3fff
	s_and_b32 s34, s54, 7
	s_mul_i32 s34, s34, 0x300000
	s_cmp_lt_u32 s54, 8
	s_cselect_b32 s30, s16, s18
	s_cselect_b32 s31, s17, s19
	s_add_u32 s30, s30, s34
	s_addc_u32 s31, s31, 0
	s_and_b32 s34, s54, 7
	s_lshl_b32 s34, s34, 6
	s_lshl_b32 s35, s55, 12
	s_add_u32 s34, s34, s35
	s_add_u32 s32, s10, s34
	s_addc_u32 s33, s11, 0
	s_lshl_b32 s34, s53, 9
	v_add_u32_e32 v240, s34, v246
	ds_read_b128 v[132:135], v240
	ds_read_b128 v[136:139], v240 offset:16
	v_cndmask_b32_e64 v236, v128, v124, s[42:43]
	v_cndmask_b32_e64 v237, v124, v128, s[42:43]
	v_cndmask_b32_e64 v238, v129, v125, s[42:43]
	v_cndmask_b32_e64 v239, v125, v129, s[42:43]
	v_add_f32_dpp v124, v236, v237 quad_perm:[2,3,0,1] row_mask:0xf bank_mask:0xf
	v_add_f32_dpp v125, v238, v239 quad_perm:[2,3,0,1] row_mask:0xf bank_mask:0xf
	v_cndmask_b32_e64 v236, v130, v126, s[42:43]
	v_cndmask_b32_e64 v237, v126, v130, s[42:43]
	v_cndmask_b32_e64 v238, v131, v127, s[42:43]
	v_cndmask_b32_e64 v239, v127, v131, s[42:43]
	v_add_f32_dpp v126, v236, v237 quad_perm:[2,3,0,1] row_mask:0xf bank_mask:0xf
	v_add_f32_dpp v127, v238, v239 quad_perm:[2,3,0,1] row_mask:0xf bank_mask:0xf
	v_cndmask_b32_e64 v236, v126, v124, s[40:41]
	v_cndmask_b32_e64 v237, v124, v126, s[40:41]
	v_cndmask_b32_e64 v238, v127, v125, s[40:41]
	v_cndmask_b32_e64 v239, v125, v127, s[40:41]
	v_add_f32_dpp v124, v236, v237 quad_perm:[1,0,3,2] row_mask:0xf bank_mask:0xf
	v_add_f32_dpp v125, v238, v239 quad_perm:[1,0,3,2] row_mask:0xf bank_mask:0xf
	s_lshl_b32 s34, s89, 9
	s_addk_i32 s34, 0x1000
	v_add_u32_e32 v243, s34, v245
	s_cmp_eq_u32 s90, 0
	s_cbranch_scc1 .Lex_ufirst
	ds_read_b64 v[236:237], v243
	s_waitcnt lgkmcnt(0)
	v_pk_add_f32 v[124:125], v[124:125], v[236:237]
.Lex_ufirst:
	ds_write_b64 v243, v[124:125]
	s_cmp_lt_u32 s8, 8
	s_cbranch_scc1 .Lex_uloop
	s_waitcnt vmcnt(0) lgkmcnt(0)
	ds_read_b64 v[140:141], v245 offset:4096
	ds_read_b64 v[142:143], v245 offset:0
	ds_read_b64 v[152:153], v245 offset:4608
	ds_read_b64 v[154:155], v245 offset:512
	ds_read_b64 v[164:165], v245 offset:5120
	ds_read_b64 v[166:167], v245 offset:1024
	ds_read_b64 v[176:177], v245 offset:5632
	ds_read_b64 v[178:179], v245 offset:1536
	ds_read_b64 v[188:189], v245 offset:6144
	ds_read_b64 v[190:191], v245 offset:2048
	ds_read_b64 v[200:201], v245 offset:6656
	ds_read_b64 v[202:203], v245 offset:2560
	ds_read_b64 v[212:213], v245 offset:7168
	ds_read_b64 v[214:215], v245 offset:3072
	ds_read_b64 v[224:225], v245 offset:7680
	ds_read_b64 v[226:227], v245 offset:3584
	s_waitcnt lgkmcnt(0)
	s_movk_i32 s36, 0
	s_mul_i32 s37, s36, s5
	s_add_i32 s37, s37, s6
	s_min_u32 s37, s37, 0x3fff
	s_lshl_b32 s37, s37, 9
	s_add_u32 s82, s14, s37
	s_addc_u32 s83, s15, 0
	global_load_dword v144, v252, s[82:83]
	global_load_dword v145, v252, s[82:83] offset:64
	v_lshlrev_b32_e32 v241, 2, v142
	v_lshlrev_b32_e32 v242, 2, v143
	global_load_dword v146, v241, s[20:21]
	global_load_dword v147, v242, s[20:21]
	global_load_dword v148, v241, s[22:23]
	global_load_dword v149, v242, s[22:23]
	s_movk_i32 s36, 1
	s_mul_i32 s37, s36, s5
	s_add_i32 s37, s37, s6
	s_min_u32 s37, s37, 0x3fff
	s_lshl_b32 s37, s37, 9
	s_add_u32 s82, s14, s37
	s_addc_u32 s83, s15, 0
	global_load_dword v156, v252, s[82:83]
	global_load_dword v157, v252, s[82:83] offset:64
	v_lshlrev_b32_e32 v241, 2, v154
	v_lshlrev_b32_e32 v242, 2, v155
	global_load_dword v158, v241, s[20:21]
	global_load_dword v159, v242, s[20:21]
	global_load_dword v160, v241, s[22:23]
	global_load_dword v161, v242, s[22:23]
	s_movk_i32 s36, 2
	s_mul_i32 s37, s36, s5
	s_add_i32 s37, s37, s6
	s_min_u32 s37, s37, 0x3fff
	s_lshl_b32 s37, s37, 9
	s_add_u32 s82, s14, s37
	s_addc_u32 s83, s15, 0
	global_load_dword v168, v252, s[82:83]
	global_load_dword v169, v252, s[82:83] offset:64
	v_lshlrev_b32_e32 v241, 2, v166
	v_lshlrev_b32_e32 v242, 2, v167
	global_load_dword v170, v241, s[20:21]
	global_load_dword v171, v242, s[20:21]
	global_load_dword v172, v241, s[22:23]
	global_load_dword v173, v242, s[22:23]
	s_movk_i32 s36, 3
	s_mul_i32 s37, s36, s5
	s_add_i32 s37, s37, s6
	s_min_u32 s37, s37, 0x3fff
	s_lshl_b32 s37, s37, 9
	s_add_u32 s82, s14, s37
	s_addc_u32 s83, s15, 0
	global_load_dword v180, v252, s[82:83]
	global_load_dword v181, v252, s[82:83] offset:64
	v_lshlrev_b32_e32 v241, 2, v178
	v_lshlrev_b32_e32 v242, 2, v179
	global_load_dword v182, v241, s[20:21]
	global_load_dword v183, v242, s[20:21]
	global_load_dword v184, v241, s[22:23]
	global_load_dword v185, v242, s[22:23]
	s_movk_i32 s36, 4
	s_mul_i32 s37, s36, s5
	s_add_i32 s37, s37, s6
	s_min_u32 s37, s37, 0x3fff
	s_lshl_b32 s37, s37, 9
	s_add_u32 s82, s14, s37
	s_addc_u32 s83, s15, 0
	global_load_dword v192, v252, s[82:83]
	global_load_dword v193, v252, s[82:83] offset:64
	v_lshlrev_b32_e32 v241, 2, v190
	v_lshlrev_b32_e32 v242, 2, v191
	global_load_dword v194, v241, s[20:21]
	global_load_dword v195, v242, s[20:21]
	global_load_dword v196, v241, s[22:23]
	global_load_dword v197, v242, s[22:23]
	s_movk_i32 s36, 5
	s_mul_i32 s37, s36, s5
	s_add_i32 s37, s37, s6
	s_min_u32 s37, s37, 0x3fff
	s_lshl_b32 s37, s37, 9
	s_add_u32 s82, s14, s37
	s_addc_u32 s83, s15, 0
	global_load_dword v204, v252, s[82:83]
	global_load_dword v205, v252, s[82:83] offset:64
	v_lshlrev_b32_e32 v241, 2, v202
	v_lshlrev_b32_e32 v242, 2, v203
	global_load_dword v206, v241, s[20:21]
	global_load_dword v207, v242, s[20:21]
	global_load_dword v208, v241, s[22:23]
	global_load_dword v209, v242, s[22:23]
	s_movk_i32 s36, 6
	s_mul_i32 s37, s36, s5
	s_add_i32 s37, s37, s6
	s_min_u32 s37, s37, 0x3fff
	s_lshl_b32 s37, s37, 9
	s_add_u32 s82, s14, s37
	s_addc_u32 s83, s15, 0
	global_load_dword v216, v252, s[82:83]
	global_load_dword v217, v252, s[82:83] offset:64
	v_lshlrev_b32_e32 v241, 2, v214
	v_lshlrev_b32_e32 v242, 2, v215
	global_load_dword v218, v241, s[20:21]
	global_load_dword v219, v242, s[20:21]
	global_load_dword v220, v241, s[22:23]
	global_load_dword v221, v242, s[22:23]
	s_movk_i32 s36, 7
	s_mul_i32 s37, s36, s5
	s_add_i32 s37, s37, s6
	s_min_u32 s37, s37, 0x3fff
	s_lshl_b32 s37, s37, 9
	s_add_u32 s82, s14, s37
	s_addc_u32 s83, s15, 0
	global_load_dword v228, v252, s[82:83]
	global_load_dword v229, v252, s[82:83] offset:64
	v_lshlrev_b32_e32 v241, 2, v226
	v_lshlrev_b32_e32 v242, 2, v227
	global_load_dword v230, v241, s[20:21]
	global_load_dword v231, v242, s[20:21]
	global_load_dword v232, v241, s[22:23]
	global_load_dword v233, v242, s[22:23]
	s_waitcnt vmcnt(0)
	v_mul_f32_e32 v140, v146, v140
	v_mul_f32_e32 v0, 0x3f3504f3, v140
	v_mov_b32_e32 v6, s67
	v_fma_f32 v2, |v0|, s66, v6
	v_fma_f32 v2, |v0|, v2, s68
	v_fma_f32 v2, |v0|, v2, s69
	v_fma_f32 v2, |v0|, v2, s70
	v_fma_f32 v2, |v0|, v2, s71
	v_fma_f32 v2, |v0|, v2, s72
	v_fma_f32 v2, |v0|, v2, |v0|
	v_mul_f32_e32 v4, 0xbfb8aa3b, v2
	v_fma_f32 v5, v2, s73, -v4
	v_rndne_f32_e32 v6, v4
	v_fmac_f32_e32 v5, 0xb2a5705f, v2
	v_sub_f32_e32 v4, v4, v6
	v_add_f32_e32 v4, v4, v5
	v_cvt_i32_f32_e32 v5, v6
	v_exp_f32_e32 v4, v4
	v_cmp_nlt_f32_e64 s[82:83], s74, v2
	v_ldexp_f32 v4, v4, v5
	s_nop 0
	v_cndmask_b32_e64 v4, 0, v4, s[82:83]
	v_cmp_ngt_f32_e64 s[82:83], s75, v2
	v_mov_b32_e32 v6, 0x7f800000
	s_nop 0
	v_cndmask_b32_e64 v3, v6, v4, s[82:83]
	v_sub_f32_e32 v3, 1.0, v3
	v_mul_f32_e32 v4, v0, v0
	v_mov_b32_e32 v6, s76
	v_fmamk_f32 v5, v4, 0xba1345e1, v6
	v_fmaak_f32 v5, v4, v5, 0xbcdac9b8
	v_fmaak_f32 v5, v4, v5, 0x3de703be
	v_fmaak_f32 v5, v4, v5, 0xbec09330
	v_fmaak_f32 v4, v4, v5, 0x3e0375d0
	v_fma_f32 v7, |v0|, v4, |v0|
	v_cmp_nlt_f32_e64 s[82:83], |v0|, 1.0
	s_nop 1
	v_cndmask_b32_e64 v3, v7, v3, s[82:83]
	v_bfi_b32 v3, s77, v3, v0
	v_mul_f32_e32 v140, 0.5, v140
	v_add_f32_e32 v3, 1.0, v3
	v_mul_f32_e32 v140, v140, v3
	v_mul_f32_e32 v140, v140, v144
	v_mul_f32_e32 v140, v148, v140
	v_mul_f32_e32 v141, v147, v141
	v_mul_f32_e32 v0, 0x3f3504f3, v141
	v_mov_b32_e32 v6, s67
	v_fma_f32 v2, |v0|, s66, v6
	v_fma_f32 v2, |v0|, v2, s68
	v_fma_f32 v2, |v0|, v2, s69
	v_fma_f32 v2, |v0|, v2, s70
	v_fma_f32 v2, |v0|, v2, s71
	v_fma_f32 v2, |v0|, v2, s72
	v_fma_f32 v2, |v0|, v2, |v0|
	v_mul_f32_e32 v4, 0xbfb8aa3b, v2
	v_fma_f32 v5, v2, s73, -v4
	v_rndne_f32_e32 v6, v4
	v_fmac_f32_e32 v5, 0xb2a5705f, v2
	v_sub_f32_e32 v4, v4, v6
	v_add_f32_e32 v4, v4, v5
	v_cvt_i32_f32_e32 v5, v6
	v_exp_f32_e32 v4, v4
	v_cmp_nlt_f32_e64 s[82:83], s74, v2
	v_ldexp_f32 v4, v4, v5
	s_nop 0
	v_cndmask_b32_e64 v4, 0, v4, s[82:83]
	v_cmp_ngt_f32_e64 s[82:83], s75, v2
	v_mov_b32_e32 v6, 0x7f800000
	s_nop 0
	v_cndmask_b32_e64 v3, v6, v4, s[82:83]
	v_sub_f32_e32 v3, 1.0, v3
	v_mul_f32_e32 v4, v0, v0
	v_mov_b32_e32 v6, s76
	v_fmamk_f32 v5, v4, 0xba1345e1, v6
	v_fmaak_f32 v5, v4, v5, 0xbcdac9b8
	v_fmaak_f32 v5, v4, v5, 0x3de703be
	v_fmaak_f32 v5, v4, v5, 0xbec09330
	v_fmaak_f32 v4, v4, v5, 0x3e0375d0
	v_fma_f32 v7, |v0|, v4, |v0|
	v_cmp_nlt_f32_e64 s[82:83], |v0|, 1.0
	s_nop 1
	v_cndmask_b32_e64 v3, v7, v3, s[82:83]
	v_bfi_b32 v3, s77, v3, v0
	v_mul_f32_e32 v141, 0.5, v141
	v_add_f32_e32 v3, 1.0, v3
	v_mul_f32_e32 v141, v141, v3
	v_mul_f32_e32 v141, v141, v145
	v_mul_f32_e32 v141, v149, v141
	ds_write_b64 v245, v[140:141] offset:4096
	v_mul_f32_e32 v152, v158, v152
	v_mul_f32_e32 v0, 0x3f3504f3, v152
	v_mov_b32_e32 v6, s67
	v_fma_f32 v2, |v0|, s66, v6
	v_fma_f32 v2, |v0|, v2, s68
	v_fma_f32 v2, |v0|, v2, s69
	v_fma_f32 v2, |v0|, v2, s70
	v_fma_f32 v2, |v0|, v2, s71
	v_fma_f32 v2, |v0|, v2, s72
	v_fma_f32 v2, |v0|, v2, |v0|
	v_mul_f32_e32 v4, 0xbfb8aa3b, v2
	v_fma_f32 v5, v2, s73, -v4
	v_rndne_f32_e32 v6, v4
	v_fmac_f32_e32 v5, 0xb2a5705f, v2
	v_sub_f32_e32 v4, v4, v6
	v_add_f32_e32 v4, v4, v5
	v_cvt_i32_f32_e32 v5, v6
	v_exp_f32_e32 v4, v4
	v_cmp_nlt_f32_e64 s[82:83], s74, v2
	v_ldexp_f32 v4, v4, v5
	s_nop 0
	v_cndmask_b32_e64 v4, 0, v4, s[82:83]
	v_cmp_ngt_f32_e64 s[82:83], s75, v2
	v_mov_b32_e32 v6, 0x7f800000
	s_nop 0
	v_cndmask_b32_e64 v3, v6, v4, s[82:83]
	v_sub_f32_e32 v3, 1.0, v3
	v_mul_f32_e32 v4, v0, v0
	v_mov_b32_e32 v6, s76
	v_fmamk_f32 v5, v4, 0xba1345e1, v6
	v_fmaak_f32 v5, v4, v5, 0xbcdac9b8
	v_fmaak_f32 v5, v4, v5, 0x3de703be
	v_fmaak_f32 v5, v4, v5, 0xbec09330
	v_fmaak_f32 v4, v4, v5, 0x3e0375d0
	v_fma_f32 v7, |v0|, v4, |v0|
	v_cmp_nlt_f32_e64 s[82:83], |v0|, 1.0
	s_nop 1
	v_cndmask_b32_e64 v3, v7, v3, s[82:83]
	v_bfi_b32 v3, s77, v3, v0
	v_mul_f32_e32 v152, 0.5, v152
	v_add_f32_e32 v3, 1.0, v3
	v_mul_f32_e32 v152, v152, v3
	v_mul_f32_e32 v152, v152, v156
	v_mul_f32_e32 v152, v160, v152
	v_mul_f32_e32 v153, v159, v153
	v_mul_f32_e32 v0, 0x3f3504f3, v153
	v_mov_b32_e32 v6, s67
	v_fma_f32 v2, |v0|, s66, v6
	v_fma_f32 v2, |v0|, v2, s68
	v_fma_f32 v2, |v0|, v2, s69
	v_fma_f32 v2, |v0|, v2, s70
	v_fma_f32 v2, |v0|, v2, s71
	v_fma_f32 v2, |v0|, v2, s72
	v_fma_f32 v2, |v0|, v2, |v0|
	v_mul_f32_e32 v4, 0xbfb8aa3b, v2
	v_fma_f32 v5, v2, s73, -v4
	v_rndne_f32_e32 v6, v4
	v_fmac_f32_e32 v5, 0xb2a5705f, v2
	v_sub_f32_e32 v4, v4, v6
	v_add_f32_e32 v4, v4, v5
	v_cvt_i32_f32_e32 v5, v6
	v_exp_f32_e32 v4, v4
	v_cmp_nlt_f32_e64 s[82:83], s74, v2
	v_ldexp_f32 v4, v4, v5
	s_nop 0
	v_cndmask_b32_e64 v4, 0, v4, s[82:83]
	v_cmp_ngt_f32_e64 s[82:83], s75, v2
	v_mov_b32_e32 v6, 0x7f800000
	s_nop 0
	v_cndmask_b32_e64 v3, v6, v4, s[82:83]
	v_sub_f32_e32 v3, 1.0, v3
	v_mul_f32_e32 v4, v0, v0
	v_mov_b32_e32 v6, s76
	v_fmamk_f32 v5, v4, 0xba1345e1, v6
	v_fmaak_f32 v5, v4, v5, 0xbcdac9b8
	v_fmaak_f32 v5, v4, v5, 0x3de703be
	v_fmaak_f32 v5, v4, v5, 0xbec09330
	v_fmaak_f32 v4, v4, v5, 0x3e0375d0
	v_fma_f32 v7, |v0|, v4, |v0|
	v_cmp_nlt_f32_e64 s[82:83], |v0|, 1.0
	s_nop 1
	v_cndmask_b32_e64 v3, v7, v3, s[82:83]
	v_bfi_b32 v3, s77, v3, v0
	v_mul_f32_e32 v153, 0.5, v153
	v_add_f32_e32 v3, 1.0, v3
	v_mul_f32_e32 v153, v153, v3
	v_mul_f32_e32 v153, v153, v157
	v_mul_f32_e32 v153, v161, v153
	ds_write_b64 v245, v[152:153] offset:4608
	v_mul_f32_e32 v164, v170, v164
	v_mul_f32_e32 v0, 0x3f3504f3, v164
	v_mov_b32_e32 v6, s67
	v_fma_f32 v2, |v0|, s66, v6
	v_fma_f32 v2, |v0|, v2, s68
	v_fma_f32 v2, |v0|, v2, s69
	v_fma_f32 v2, |v0|, v2, s70
	v_fma_f32 v2, |v0|, v2, s71
	v_fma_f32 v2, |v0|, v2, s72
	v_fma_f32 v2, |v0|, v2, |v0|
	v_mul_f32_e32 v4, 0xbfb8aa3b, v2
	v_fma_f32 v5, v2, s73, -v4
	v_rndne_f32_e32 v6, v4
	v_fmac_f32_e32 v5, 0xb2a5705f, v2
	v_sub_f32_e32 v4, v4, v6
	v_add_f32_e32 v4, v4, v5
	v_cvt_i32_f32_e32 v5, v6
	v_exp_f32_e32 v4, v4
	v_cmp_nlt_f32_e64 s[82:83], s74, v2
	v_ldexp_f32 v4, v4, v5
	s_nop 0
	v_cndmask_b32_e64 v4, 0, v4, s[82:83]
	v_cmp_ngt_f32_e64 s[82:83], s75, v2
	v_mov_b32_e32 v6, 0x7f800000
	s_nop 0
	v_cndmask_b32_e64 v3, v6, v4, s[82:83]
	v_sub_f32_e32 v3, 1.0, v3
	v_mul_f32_e32 v4, v0, v0
	v_mov_b32_e32 v6, s76
	v_fmamk_f32 v5, v4, 0xba1345e1, v6
	v_fmaak_f32 v5, v4, v5, 0xbcdac9b8
	v_fmaak_f32 v5, v4, v5, 0x3de703be
	v_fmaak_f32 v5, v4, v5, 0xbec09330
	v_fmaak_f32 v4, v4, v5, 0x3e0375d0
	v_fma_f32 v7, |v0|, v4, |v0|
	v_cmp_nlt_f32_e64 s[82:83], |v0|, 1.0
	s_nop 1
	v_cndmask_b32_e64 v3, v7, v3, s[82:83]
	v_bfi_b32 v3, s77, v3, v0
	v_mul_f32_e32 v164, 0.5, v164
	v_add_f32_e32 v3, 1.0, v3
	v_mul_f32_e32 v164, v164, v3
	v_mul_f32_e32 v164, v164, v168
	v_mul_f32_e32 v164, v172, v164
	v_mul_f32_e32 v165, v171, v165
	v_mul_f32_e32 v0, 0x3f3504f3, v165
	v_mov_b32_e32 v6, s67
	v_fma_f32 v2, |v0|, s66, v6
	v_fma_f32 v2, |v0|, v2, s68
	v_fma_f32 v2, |v0|, v2, s69
	v_fma_f32 v2, |v0|, v2, s70
	v_fma_f32 v2, |v0|, v2, s71
	v_fma_f32 v2, |v0|, v2, s72
	v_fma_f32 v2, |v0|, v2, |v0|
	v_mul_f32_e32 v4, 0xbfb8aa3b, v2
	v_fma_f32 v5, v2, s73, -v4
	v_rndne_f32_e32 v6, v4
	v_fmac_f32_e32 v5, 0xb2a5705f, v2
	v_sub_f32_e32 v4, v4, v6
	v_add_f32_e32 v4, v4, v5
	v_cvt_i32_f32_e32 v5, v6
	v_exp_f32_e32 v4, v4
	v_cmp_nlt_f32_e64 s[82:83], s74, v2
	v_ldexp_f32 v4, v4, v5
	s_nop 0
	v_cndmask_b32_e64 v4, 0, v4, s[82:83]
	v_cmp_ngt_f32_e64 s[82:83], s75, v2
	v_mov_b32_e32 v6, 0x7f800000
	s_nop 0
	v_cndmask_b32_e64 v3, v6, v4, s[82:83]
	v_sub_f32_e32 v3, 1.0, v3
	v_mul_f32_e32 v4, v0, v0
	v_mov_b32_e32 v6, s76
	v_fmamk_f32 v5, v4, 0xba1345e1, v6
	v_fmaak_f32 v5, v4, v5, 0xbcdac9b8
	v_fmaak_f32 v5, v4, v5, 0x3de703be
	v_fmaak_f32 v5, v4, v5, 0xbec09330
	v_fmaak_f32 v4, v4, v5, 0x3e0375d0
	v_fma_f32 v7, |v0|, v4, |v0|
	v_cmp_nlt_f32_e64 s[82:83], |v0|, 1.0
	s_nop 1
	v_cndmask_b32_e64 v3, v7, v3, s[82:83]
	v_bfi_b32 v3, s77, v3, v0
	v_mul_f32_e32 v165, 0.5, v165
	v_add_f32_e32 v3, 1.0, v3
	v_mul_f32_e32 v165, v165, v3
	v_mul_f32_e32 v165, v165, v169
	v_mul_f32_e32 v165, v173, v165
	ds_write_b64 v245, v[164:165] offset:5120
	v_mul_f32_e32 v176, v182, v176
	v_mul_f32_e32 v0, 0x3f3504f3, v176
	v_mov_b32_e32 v6, s67
	v_fma_f32 v2, |v0|, s66, v6
	v_fma_f32 v2, |v0|, v2, s68
	v_fma_f32 v2, |v0|, v2, s69
	v_fma_f32 v2, |v0|, v2, s70
	v_fma_f32 v2, |v0|, v2, s71
	v_fma_f32 v2, |v0|, v2, s72
	v_fma_f32 v2, |v0|, v2, |v0|
	v_mul_f32_e32 v4, 0xbfb8aa3b, v2
	v_fma_f32 v5, v2, s73, -v4
	v_rndne_f32_e32 v6, v4
	v_fmac_f32_e32 v5, 0xb2a5705f, v2
	v_sub_f32_e32 v4, v4, v6
	v_add_f32_e32 v4, v4, v5
	v_cvt_i32_f32_e32 v5, v6
	v_exp_f32_e32 v4, v4
	v_cmp_nlt_f32_e64 s[82:83], s74, v2
	v_ldexp_f32 v4, v4, v5
	s_nop 0
	v_cndmask_b32_e64 v4, 0, v4, s[82:83]
	v_cmp_ngt_f32_e64 s[82:83], s75, v2
	v_mov_b32_e32 v6, 0x7f800000
	s_nop 0
	v_cndmask_b32_e64 v3, v6, v4, s[82:83]
	v_sub_f32_e32 v3, 1.0, v3
	v_mul_f32_e32 v4, v0, v0
	v_mov_b32_e32 v6, s76
	v_fmamk_f32 v5, v4, 0xba1345e1, v6
	v_fmaak_f32 v5, v4, v5, 0xbcdac9b8
	v_fmaak_f32 v5, v4, v5, 0x3de703be
	v_fmaak_f32 v5, v4, v5, 0xbec09330
	v_fmaak_f32 v4, v4, v5, 0x3e0375d0
	v_fma_f32 v7, |v0|, v4, |v0|
	v_cmp_nlt_f32_e64 s[82:83], |v0|, 1.0
	s_nop 1
	v_cndmask_b32_e64 v3, v7, v3, s[82:83]
	v_bfi_b32 v3, s77, v3, v0
	v_mul_f32_e32 v176, 0.5, v176
	v_add_f32_e32 v3, 1.0, v3
	v_mul_f32_e32 v176, v176, v3
	v_mul_f32_e32 v176, v176, v180
	v_mul_f32_e32 v176, v184, v176
	v_mul_f32_e32 v177, v183, v177
	v_mul_f32_e32 v0, 0x3f3504f3, v177
	v_mov_b32_e32 v6, s67
	v_fma_f32 v2, |v0|, s66, v6
	v_fma_f32 v2, |v0|, v2, s68
	v_fma_f32 v2, |v0|, v2, s69
	v_fma_f32 v2, |v0|, v2, s70
	v_fma_f32 v2, |v0|, v2, s71
	v_fma_f32 v2, |v0|, v2, s72
	v_fma_f32 v2, |v0|, v2, |v0|
	v_mul_f32_e32 v4, 0xbfb8aa3b, v2
	v_fma_f32 v5, v2, s73, -v4
	v_rndne_f32_e32 v6, v4
	v_fmac_f32_e32 v5, 0xb2a5705f, v2
	v_sub_f32_e32 v4, v4, v6
	v_add_f32_e32 v4, v4, v5
	v_cvt_i32_f32_e32 v5, v6
	v_exp_f32_e32 v4, v4
	v_cmp_nlt_f32_e64 s[82:83], s74, v2
	v_ldexp_f32 v4, v4, v5
	s_nop 0
	v_cndmask_b32_e64 v4, 0, v4, s[82:83]
	v_cmp_ngt_f32_e64 s[82:83], s75, v2
	v_mov_b32_e32 v6, 0x7f800000
	s_nop 0
	v_cndmask_b32_e64 v3, v6, v4, s[82:83]
	v_sub_f32_e32 v3, 1.0, v3
	v_mul_f32_e32 v4, v0, v0
	v_mov_b32_e32 v6, s76
	v_fmamk_f32 v5, v4, 0xba1345e1, v6
	v_fmaak_f32 v5, v4, v5, 0xbcdac9b8
	v_fmaak_f32 v5, v4, v5, 0x3de703be
	v_fmaak_f32 v5, v4, v5, 0xbec09330
	v_fmaak_f32 v4, v4, v5, 0x3e0375d0
	v_fma_f32 v7, |v0|, v4, |v0|
	v_cmp_nlt_f32_e64 s[82:83], |v0|, 1.0
	s_nop 1
	v_cndmask_b32_e64 v3, v7, v3, s[82:83]
	v_bfi_b32 v3, s77, v3, v0
	v_mul_f32_e32 v177, 0.5, v177
	v_add_f32_e32 v3, 1.0, v3
	v_mul_f32_e32 v177, v177, v3
	v_mul_f32_e32 v177, v177, v181
	v_mul_f32_e32 v177, v185, v177
	ds_write_b64 v245, v[176:177] offset:5632
	v_mul_f32_e32 v188, v194, v188
	v_mul_f32_e32 v0, 0x3f3504f3, v188
	v_mov_b32_e32 v6, s67
	v_fma_f32 v2, |v0|, s66, v6
	v_fma_f32 v2, |v0|, v2, s68
	v_fma_f32 v2, |v0|, v2, s69
	v_fma_f32 v2, |v0|, v2, s70
	v_fma_f32 v2, |v0|, v2, s71
	v_fma_f32 v2, |v0|, v2, s72
	v_fma_f32 v2, |v0|, v2, |v0|
	v_mul_f32_e32 v4, 0xbfb8aa3b, v2
	v_fma_f32 v5, v2, s73, -v4
	v_rndne_f32_e32 v6, v4
	v_fmac_f32_e32 v5, 0xb2a5705f, v2
	v_sub_f32_e32 v4, v4, v6
	v_add_f32_e32 v4, v4, v5
	v_cvt_i32_f32_e32 v5, v6
	v_exp_f32_e32 v4, v4
	v_cmp_nlt_f32_e64 s[82:83], s74, v2
	v_ldexp_f32 v4, v4, v5
	s_nop 0
	v_cndmask_b32_e64 v4, 0, v4, s[82:83]
	v_cmp_ngt_f32_e64 s[82:83], s75, v2
	v_mov_b32_e32 v6, 0x7f800000
	s_nop 0
	v_cndmask_b32_e64 v3, v6, v4, s[82:83]
	v_sub_f32_e32 v3, 1.0, v3
	v_mul_f32_e32 v4, v0, v0
	v_mov_b32_e32 v6, s76
	v_fmamk_f32 v5, v4, 0xba1345e1, v6
	v_fmaak_f32 v5, v4, v5, 0xbcdac9b8
	v_fmaak_f32 v5, v4, v5, 0x3de703be
	v_fmaak_f32 v5, v4, v5, 0xbec09330
	v_fmaak_f32 v4, v4, v5, 0x3e0375d0
	v_fma_f32 v7, |v0|, v4, |v0|
	v_cmp_nlt_f32_e64 s[82:83], |v0|, 1.0
	s_nop 1
	v_cndmask_b32_e64 v3, v7, v3, s[82:83]
	v_bfi_b32 v3, s77, v3, v0
	v_mul_f32_e32 v188, 0.5, v188
	v_add_f32_e32 v3, 1.0, v3
	v_mul_f32_e32 v188, v188, v3
	v_mul_f32_e32 v188, v188, v192
	v_mul_f32_e32 v188, v196, v188
	v_mul_f32_e32 v189, v195, v189
	v_mul_f32_e32 v0, 0x3f3504f3, v189
	v_mov_b32_e32 v6, s67
	v_fma_f32 v2, |v0|, s66, v6
	v_fma_f32 v2, |v0|, v2, s68
	v_fma_f32 v2, |v0|, v2, s69
	v_fma_f32 v2, |v0|, v2, s70
	v_fma_f32 v2, |v0|, v2, s71
	v_fma_f32 v2, |v0|, v2, s72
	v_fma_f32 v2, |v0|, v2, |v0|
	v_mul_f32_e32 v4, 0xbfb8aa3b, v2
	v_fma_f32 v5, v2, s73, -v4
	v_rndne_f32_e32 v6, v4
	v_fmac_f32_e32 v5, 0xb2a5705f, v2
	v_sub_f32_e32 v4, v4, v6
	v_add_f32_e32 v4, v4, v5
	v_cvt_i32_f32_e32 v5, v6
	v_exp_f32_e32 v4, v4
	v_cmp_nlt_f32_e64 s[82:83], s74, v2
	v_ldexp_f32 v4, v4, v5
	s_nop 0
	v_cndmask_b32_e64 v4, 0, v4, s[82:83]
	v_cmp_ngt_f32_e64 s[82:83], s75, v2
	v_mov_b32_e32 v6, 0x7f800000
	s_nop 0
	v_cndmask_b32_e64 v3, v6, v4, s[82:83]
	v_sub_f32_e32 v3, 1.0, v3
	v_mul_f32_e32 v4, v0, v0
	v_mov_b32_e32 v6, s76
	v_fmamk_f32 v5, v4, 0xba1345e1, v6
	v_fmaak_f32 v5, v4, v5, 0xbcdac9b8
	v_fmaak_f32 v5, v4, v5, 0x3de703be
	v_fmaak_f32 v5, v4, v5, 0xbec09330
	v_fmaak_f32 v4, v4, v5, 0x3e0375d0
	v_fma_f32 v7, |v0|, v4, |v0|
	v_cmp_nlt_f32_e64 s[82:83], |v0|, 1.0
	s_nop 1
	v_cndmask_b32_e64 v3, v7, v3, s[82:83]
	v_bfi_b32 v3, s77, v3, v0
	v_mul_f32_e32 v189, 0.5, v189
	v_add_f32_e32 v3, 1.0, v3
	v_mul_f32_e32 v189, v189, v3
	v_mul_f32_e32 v189, v189, v193
	v_mul_f32_e32 v189, v197, v189
	ds_write_b64 v245, v[188:189] offset:6144
	v_mul_f32_e32 v200, v206, v200
	v_mul_f32_e32 v0, 0x3f3504f3, v200
	v_mov_b32_e32 v6, s67
	v_fma_f32 v2, |v0|, s66, v6
	v_fma_f32 v2, |v0|, v2, s68
	v_fma_f32 v2, |v0|, v2, s69
	v_fma_f32 v2, |v0|, v2, s70
	v_fma_f32 v2, |v0|, v2, s71
	v_fma_f32 v2, |v0|, v2, s72
	v_fma_f32 v2, |v0|, v2, |v0|
	v_mul_f32_e32 v4, 0xbfb8aa3b, v2
	v_fma_f32 v5, v2, s73, -v4
	v_rndne_f32_e32 v6, v4
	v_fmac_f32_e32 v5, 0xb2a5705f, v2
	v_sub_f32_e32 v4, v4, v6
	v_add_f32_e32 v4, v4, v5
	v_cvt_i32_f32_e32 v5, v6
	v_exp_f32_e32 v4, v4
	v_cmp_nlt_f32_e64 s[82:83], s74, v2
	v_ldexp_f32 v4, v4, v5
	s_nop 0
	v_cndmask_b32_e64 v4, 0, v4, s[82:83]
	v_cmp_ngt_f32_e64 s[82:83], s75, v2
	v_mov_b32_e32 v6, 0x7f800000
	s_nop 0
	v_cndmask_b32_e64 v3, v6, v4, s[82:83]
	v_sub_f32_e32 v3, 1.0, v3
	v_mul_f32_e32 v4, v0, v0
	v_mov_b32_e32 v6, s76
	v_fmamk_f32 v5, v4, 0xba1345e1, v6
	v_fmaak_f32 v5, v4, v5, 0xbcdac9b8
	v_fmaak_f32 v5, v4, v5, 0x3de703be
	v_fmaak_f32 v5, v4, v5, 0xbec09330
	v_fmaak_f32 v4, v4, v5, 0x3e0375d0
	v_fma_f32 v7, |v0|, v4, |v0|
	v_cmp_nlt_f32_e64 s[82:83], |v0|, 1.0
	s_nop 1
	v_cndmask_b32_e64 v3, v7, v3, s[82:83]
	v_bfi_b32 v3, s77, v3, v0
	v_mul_f32_e32 v200, 0.5, v200
	v_add_f32_e32 v3, 1.0, v3
	v_mul_f32_e32 v200, v200, v3
	v_mul_f32_e32 v200, v200, v204
	v_mul_f32_e32 v200, v208, v200
	v_mul_f32_e32 v201, v207, v201
	v_mul_f32_e32 v0, 0x3f3504f3, v201
	v_mov_b32_e32 v6, s67
	v_fma_f32 v2, |v0|, s66, v6
	v_fma_f32 v2, |v0|, v2, s68
	v_fma_f32 v2, |v0|, v2, s69
	v_fma_f32 v2, |v0|, v2, s70
	v_fma_f32 v2, |v0|, v2, s71
	v_fma_f32 v2, |v0|, v2, s72
	v_fma_f32 v2, |v0|, v2, |v0|
	v_mul_f32_e32 v4, 0xbfb8aa3b, v2
	v_fma_f32 v5, v2, s73, -v4
	v_rndne_f32_e32 v6, v4
	v_fmac_f32_e32 v5, 0xb2a5705f, v2
	v_sub_f32_e32 v4, v4, v6
	v_add_f32_e32 v4, v4, v5
	v_cvt_i32_f32_e32 v5, v6
	v_exp_f32_e32 v4, v4
	v_cmp_nlt_f32_e64 s[82:83], s74, v2
	v_ldexp_f32 v4, v4, v5
	s_nop 0
	v_cndmask_b32_e64 v4, 0, v4, s[82:83]
	v_cmp_ngt_f32_e64 s[82:83], s75, v2
	v_mov_b32_e32 v6, 0x7f800000
	s_nop 0
	v_cndmask_b32_e64 v3, v6, v4, s[82:83]
	v_sub_f32_e32 v3, 1.0, v3
	v_mul_f32_e32 v4, v0, v0
	v_mov_b32_e32 v6, s76
	v_fmamk_f32 v5, v4, 0xba1345e1, v6
	v_fmaak_f32 v5, v4, v5, 0xbcdac9b8
	v_fmaak_f32 v5, v4, v5, 0x3de703be
	v_fmaak_f32 v5, v4, v5, 0xbec09330
	v_fmaak_f32 v4, v4, v5, 0x3e0375d0
	v_fma_f32 v7, |v0|, v4, |v0|
	v_cmp_nlt_f32_e64 s[82:83], |v0|, 1.0
	s_nop 1
	v_cndmask_b32_e64 v3, v7, v3, s[82:83]
	v_bfi_b32 v3, s77, v3, v0
	v_mul_f32_e32 v201, 0.5, v201
	v_add_f32_e32 v3, 1.0, v3
	v_mul_f32_e32 v201, v201, v3
	v_mul_f32_e32 v201, v201, v205
	v_mul_f32_e32 v201, v209, v201
	ds_write_b64 v245, v[200:201] offset:6656
	v_mul_f32_e32 v212, v218, v212
	v_mul_f32_e32 v0, 0x3f3504f3, v212
	v_mov_b32_e32 v6, s67
	v_fma_f32 v2, |v0|, s66, v6
	v_fma_f32 v2, |v0|, v2, s68
	v_fma_f32 v2, |v0|, v2, s69
	v_fma_f32 v2, |v0|, v2, s70
	v_fma_f32 v2, |v0|, v2, s71
	v_fma_f32 v2, |v0|, v2, s72
	v_fma_f32 v2, |v0|, v2, |v0|
	v_mul_f32_e32 v4, 0xbfb8aa3b, v2
	v_fma_f32 v5, v2, s73, -v4
	v_rndne_f32_e32 v6, v4
	v_fmac_f32_e32 v5, 0xb2a5705f, v2
	v_sub_f32_e32 v4, v4, v6
	v_add_f32_e32 v4, v4, v5
	v_cvt_i32_f32_e32 v5, v6
	v_exp_f32_e32 v4, v4
	v_cmp_nlt_f32_e64 s[82:83], s74, v2
	v_ldexp_f32 v4, v4, v5
	s_nop 0
	v_cndmask_b32_e64 v4, 0, v4, s[82:83]
	v_cmp_ngt_f32_e64 s[82:83], s75, v2
	v_mov_b32_e32 v6, 0x7f800000
	s_nop 0
	v_cndmask_b32_e64 v3, v6, v4, s[82:83]
	v_sub_f32_e32 v3, 1.0, v3
	v_mul_f32_e32 v4, v0, v0
	v_mov_b32_e32 v6, s76
	v_fmamk_f32 v5, v4, 0xba1345e1, v6
	v_fmaak_f32 v5, v4, v5, 0xbcdac9b8
	v_fmaak_f32 v5, v4, v5, 0x3de703be
	v_fmaak_f32 v5, v4, v5, 0xbec09330
	v_fmaak_f32 v4, v4, v5, 0x3e0375d0
	v_fma_f32 v7, |v0|, v4, |v0|
	v_cmp_nlt_f32_e64 s[82:83], |v0|, 1.0
	s_nop 1
	v_cndmask_b32_e64 v3, v7, v3, s[82:83]
	v_bfi_b32 v3, s77, v3, v0
	v_mul_f32_e32 v212, 0.5, v212
	v_add_f32_e32 v3, 1.0, v3
	v_mul_f32_e32 v212, v212, v3
	v_mul_f32_e32 v212, v212, v216
	v_mul_f32_e32 v212, v220, v212
	v_mul_f32_e32 v213, v219, v213
	v_mul_f32_e32 v0, 0x3f3504f3, v213
	v_mov_b32_e32 v6, s67
	v_fma_f32 v2, |v0|, s66, v6
	v_fma_f32 v2, |v0|, v2, s68
	v_fma_f32 v2, |v0|, v2, s69
	v_fma_f32 v2, |v0|, v2, s70
	v_fma_f32 v2, |v0|, v2, s71
	v_fma_f32 v2, |v0|, v2, s72
	v_fma_f32 v2, |v0|, v2, |v0|
	v_mul_f32_e32 v4, 0xbfb8aa3b, v2
	v_fma_f32 v5, v2, s73, -v4
	v_rndne_f32_e32 v6, v4
	v_fmac_f32_e32 v5, 0xb2a5705f, v2
	v_sub_f32_e32 v4, v4, v6
	v_add_f32_e32 v4, v4, v5
	v_cvt_i32_f32_e32 v5, v6
	v_exp_f32_e32 v4, v4
	v_cmp_nlt_f32_e64 s[82:83], s74, v2
	v_ldexp_f32 v4, v4, v5
	s_nop 0
	v_cndmask_b32_e64 v4, 0, v4, s[82:83]
	v_cmp_ngt_f32_e64 s[82:83], s75, v2
	v_mov_b32_e32 v6, 0x7f800000
	s_nop 0
	v_cndmask_b32_e64 v3, v6, v4, s[82:83]
	v_sub_f32_e32 v3, 1.0, v3
	v_mul_f32_e32 v4, v0, v0
	v_mov_b32_e32 v6, s76
	v_fmamk_f32 v5, v4, 0xba1345e1, v6
	v_fmaak_f32 v5, v4, v5, 0xbcdac9b8
	v_fmaak_f32 v5, v4, v5, 0x3de703be
	v_fmaak_f32 v5, v4, v5, 0xbec09330
	v_fmaak_f32 v4, v4, v5, 0x3e0375d0
	v_fma_f32 v7, |v0|, v4, |v0|
	v_cmp_nlt_f32_e64 s[82:83], |v0|, 1.0
	s_nop 1
	v_cndmask_b32_e64 v3, v7, v3, s[82:83]
	v_bfi_b32 v3, s77, v3, v0
	v_mul_f32_e32 v213, 0.5, v213
	v_add_f32_e32 v3, 1.0, v3
	v_mul_f32_e32 v213, v213, v3
	v_mul_f32_e32 v213, v213, v217
	v_mul_f32_e32 v213, v221, v213
	ds_write_b64 v245, v[212:213] offset:7168
	v_mul_f32_e32 v224, v230, v224
	v_mul_f32_e32 v0, 0x3f3504f3, v224
	v_mov_b32_e32 v6, s67
	v_fma_f32 v2, |v0|, s66, v6
	v_fma_f32 v2, |v0|, v2, s68
	v_fma_f32 v2, |v0|, v2, s69
	v_fma_f32 v2, |v0|, v2, s70
	v_fma_f32 v2, |v0|, v2, s71
	v_fma_f32 v2, |v0|, v2, s72
	v_fma_f32 v2, |v0|, v2, |v0|
	v_mul_f32_e32 v4, 0xbfb8aa3b, v2
	v_fma_f32 v5, v2, s73, -v4
	v_rndne_f32_e32 v6, v4
	v_fmac_f32_e32 v5, 0xb2a5705f, v2
	v_sub_f32_e32 v4, v4, v6
	v_add_f32_e32 v4, v4, v5
	v_cvt_i32_f32_e32 v5, v6
	v_exp_f32_e32 v4, v4
	v_cmp_nlt_f32_e64 s[82:83], s74, v2
	v_ldexp_f32 v4, v4, v5
	s_nop 0
	v_cndmask_b32_e64 v4, 0, v4, s[82:83]
	v_cmp_ngt_f32_e64 s[82:83], s75, v2
	v_mov_b32_e32 v6, 0x7f800000
	s_nop 0
	v_cndmask_b32_e64 v3, v6, v4, s[82:83]
	v_sub_f32_e32 v3, 1.0, v3
	v_mul_f32_e32 v4, v0, v0
	v_mov_b32_e32 v6, s76
	v_fmamk_f32 v5, v4, 0xba1345e1, v6
	v_fmaak_f32 v5, v4, v5, 0xbcdac9b8
	v_fmaak_f32 v5, v4, v5, 0x3de703be
	v_fmaak_f32 v5, v4, v5, 0xbec09330
	v_fmaak_f32 v4, v4, v5, 0x3e0375d0
	v_fma_f32 v7, |v0|, v4, |v0|
	v_cmp_nlt_f32_e64 s[82:83], |v0|, 1.0
	s_nop 1
	v_cndmask_b32_e64 v3, v7, v3, s[82:83]
	v_bfi_b32 v3, s77, v3, v0
	v_mul_f32_e32 v224, 0.5, v224
	v_add_f32_e32 v3, 1.0, v3
	v_mul_f32_e32 v224, v224, v3
	v_mul_f32_e32 v224, v224, v228
	v_mul_f32_e32 v224, v232, v224
	v_mul_f32_e32 v225, v231, v225
	v_mul_f32_e32 v0, 0x3f3504f3, v225
	v_mov_b32_e32 v6, s67
	v_fma_f32 v2, |v0|, s66, v6
	v_fma_f32 v2, |v0|, v2, s68
	v_fma_f32 v2, |v0|, v2, s69
	v_fma_f32 v2, |v0|, v2, s70
	v_fma_f32 v2, |v0|, v2, s71
	v_fma_f32 v2, |v0|, v2, s72
	v_fma_f32 v2, |v0|, v2, |v0|
	v_mul_f32_e32 v4, 0xbfb8aa3b, v2
	v_fma_f32 v5, v2, s73, -v4
	v_rndne_f32_e32 v6, v4
	v_fmac_f32_e32 v5, 0xb2a5705f, v2
	v_sub_f32_e32 v4, v4, v6
	v_add_f32_e32 v4, v4, v5
	v_cvt_i32_f32_e32 v5, v6
	v_exp_f32_e32 v4, v4
	v_cmp_nlt_f32_e64 s[82:83], s74, v2
	v_ldexp_f32 v4, v4, v5
	s_nop 0
	v_cndmask_b32_e64 v4, 0, v4, s[82:83]
	v_cmp_ngt_f32_e64 s[82:83], s75, v2
	v_mov_b32_e32 v6, 0x7f800000
	s_nop 0
	v_cndmask_b32_e64 v3, v6, v4, s[82:83]
	v_sub_f32_e32 v3, 1.0, v3
	v_mul_f32_e32 v4, v0, v0
	v_mov_b32_e32 v6, s76
	v_fmamk_f32 v5, v4, 0xba1345e1, v6
	v_fmaak_f32 v5, v4, v5, 0xbcdac9b8
	v_fmaak_f32 v5, v4, v5, 0x3de703be
	v_fmaak_f32 v5, v4, v5, 0xbec09330
	v_fmaak_f32 v4, v4, v5, 0x3e0375d0
	v_fma_f32 v7, |v0|, v4, |v0|
	v_cmp_nlt_f32_e64 s[82:83], |v0|, 1.0
	s_nop 1
	v_cndmask_b32_e64 v3, v7, v3, s[82:83]
	v_bfi_b32 v3, s77, v3, v0
	v_mul_f32_e32 v225, 0.5, v225
	v_add_f32_e32 v3, 1.0, v3
	v_mul_f32_e32 v225, v225, v3
	v_mul_f32_e32 v225, v225, v229
	v_mul_f32_e32 v225, v233, v225
	ds_write_b64 v245, v[224:225] offset:7680
	s_waitcnt lgkmcnt(0)
	s_mov_b32 s8, 8
	s_mov_b32 s7, 0
	s_mov_b32 s54, 8
	s_mov_b32 s53, 0
	s_mul_i32 s55, s53, s5
	s_add_i32 s55, s55, s6
	s_min_u32 s55, s55, 0x3fff
	s_and_b32 s34, s54, 7
	s_mul_i32 s34, s34, 0x300000
	s_cmp_lt_u32 s54, 8
	s_cselect_b32 s30, s16, s18
	s_cselect_b32 s31, s17, s19
	s_add_u32 s30, s30, s34
	s_addc_u32 s31, s31, 0
	s_and_b32 s34, s54, 7
	s_lshl_b32 s34, s34, 6
	s_lshl_b32 s35, s55, 12
	s_add_u32 s34, s34, s35
	s_add_u32 s32, s24, s34
	s_addc_u32 s33, s25, 0
	s_and_b32 s34, s54, 7
	s_lshl_b32 s34, s34, 7
	s_lshr_b32 s35, s55, 13
	s_mul_i32 s35, s35, 0xc000
	s_add_u32 s35, s35, s34
	s_add_u32 s35, s35, 0xa000
	s_add_u32 s58, s26, s35
	s_addc_u32 s59, s27, 0
	s_lshl_b32 s35, s55, 13
	s_add_u32 s35, s35, s34
	s_add_u32 s60, s28, s35
	s_addc_u32 s61, s29, 0
	s_mul_i32 s34, s53, s5
	s_add_i32 s34, s34, s6
	s_cmp_lt_u32 s34, 0x4000
	s_cselect_b32 s57, 1, 0
	s_mov_b32 s78, s60
	s_mov_b32 s79, s61
	s_mov_b32 s80, s57
	s_lshl_b32 s34, s53, 9
	v_add_u32_e32 v240, s34, v246
	ds_read_b128 v[132:135], v240
	ds_read_b128 v[136:139], v240 offset:16
	s_waitcnt lgkmcnt(0)
	global_load_dwordx2 v[96:97], v248, s[32:33]
	global_load_dwordx4 v[98:101], v249, s[58:59]
	v_mad_u32_u24 v241, v132, s52, v244
	global_load_dwordx4 v[140:143], v241, s[30:31]
	global_load_dwordx4 v[144:147], v241, s[30:31] offset:64
	global_load_dwordx4 v[148:151], v241, s[30:31] offset:128
	v_mad_u32_u24 v241, v133, s52, v244
	global_load_dwordx4 v[152:155], v241, s[30:31]
	global_load_dwordx4 v[156:159], v241, s[30:31] offset:64
	global_load_dwordx4 v[160:163], v241, s[30:31] offset:128
	v_mad_u32_u24 v241, v134, s52, v244
	global_load_dwordx4 v[164:167], v241, s[30:31]
	global_load_dwordx4 v[168:171], v241, s[30:31] offset:64
	global_load_dwordx4 v[172:175], v241, s[30:31] offset:128
	v_mad_u32_u24 v241, v135, s52, v244
	global_load_dwordx4 v[176:179], v241, s[30:31]
	global_load_dwordx4 v[180:183], v241, s[30:31] offset:64
	global_load_dwordx4 v[184:187], v241, s[30:31] offset:128
	v_mad_u32_u24 v241, v136, s52, v244
	global_load_dwordx4 v[188:191], v241, s[30:31]
	global_load_dwordx4 v[192:195], v241, s[30:31] offset:64
	global_load_dwordx4 v[196:199], v241, s[30:31] offset:128
	v_mad_u32_u24 v241, v137, s52, v244
	global_load_dwordx4 v[200:203], v241, s[30:31]
	global_load_dwordx4 v[204:207], v241, s[30:31] offset:64
	global_load_dwordx4 v[208:211], v241, s[30:31] offset:128
	v_mad_u32_u24 v241, v138, s52, v244
	global_load_dwordx4 v[212:215], v241, s[30:31]
	global_load_dwordx4 v[216:219], v241, s[30:31] offset:64
	global_load_dwordx4 v[220:223], v241, s[30:31] offset:128
	v_mad_u32_u24 v241, v139, s52, v244
	global_load_dwordx4 v[224:227], v241, s[30:31]
	global_load_dwordx4 v[228:231], v241, s[30:31] offset:64
	global_load_dwordx4 v[232:235], v241, s[30:31] offset:128
	global_load_dword v108, v254, s[28:29]
	s_add_i32 s53, s7, 1
	s_mov_b32 s54, s8
	s_cmp_eq_u32 s53, 8
	s_cselect_b32 s53, 0, s53
	s_cselect_b32 s34, 1, 0
	s_add_i32 s54, s54, s34
	s_mul_i32 s55, s53, s5
	s_add_i32 s55, s55, s6
	s_min_u32 s55, s55, 0x3fff
	s_and_b32 s34, s54, 7
	s_mul_i32 s34, s34, 0x300000
	s_cmp_lt_u32 s54, 8
	s_cselect_b32 s30, s16, s18
	s_cselect_b32 s31, s17, s19
	s_add_u32 s30, s30, s34
	s_addc_u32 s31, s31, 0
	s_and_b32 s34, s54, 7
	s_lshl_b32 s34, s34, 6
	s_lshl_b32 s35, s55, 12
	s_add_u32 s34, s34, s35
	s_add_u32 s32, s24, s34
	s_addc_u32 s33, s25, 0
	s_and_b32 s34, s54, 7
	s_lshl_b32 s34, s34, 7
	s_lshr_b32 s35, s55, 13
	s_mul_i32 s35, s35, 0xc000
	s_add_u32 s35, s35, s34
	s_add_u32 s35, s35, 0xa000
	s_add_u32 s58, s26, s35
	s_addc_u32 s59, s27, 0
	s_lshl_b32 s35, s55, 13
	s_add_u32 s35, s35, s34
	s_add_u32 s60, s28, s35
	s_addc_u32 s61, s29, 0
	s_mul_i32 s34, s53, s5
	s_add_i32 s34, s34, s6
	s_cmp_lt_u32 s34, 0x4000
	s_cselect_b32 s57, 1, 0
	s_lshl_b32 s34, s53, 9
	v_add_u32_e32 v240, s34, v246
	ds_read_b128 v[132:135], v240
	ds_read_b128 v[136:139], v240 offset:16
.Lex_vloop:
	s_lshl_b32 s34, s7, 9
	v_add_u32_e32 v243, s34, v255
	ds_read_b128 v[124:127], v243
	ds_read_b128 v[128:131], v243 offset:16
	s_waitcnt vmcnt(25)
	v_mov_b32_e32 v102, v96
	v_mov_b32_e32 v103, v97
	v_mov_b32_e32 v104, v98
	v_mov_b32_e32 v105, v99
	v_mov_b32_e32 v106, v100
	v_mov_b32_e32 v107, v101
	s_waitcnt lgkmcnt(0)
	s_waitcnt vmcnt(22)
	v_cvt_scalef32_pk32_f32_fp6 v[0:31], v[140:145], 1.0
	v_pk_mul_f32 v[32:33], v[124:125], v[0:1] op_sel_hi:[0,1]
	v_pk_mul_f32 v[34:35], v[124:125], v[2:3] op_sel_hi:[0,1]
	v_pk_mul_f32 v[36:37], v[124:125], v[4:5] op_sel_hi:[0,1]
	v_pk_mul_f32 v[38:39], v[124:125], v[6:7] op_sel_hi:[0,1]
	v_pk_mul_f32 v[40:41], v[124:125], v[8:9] op_sel_hi:[0,1]
	v_pk_mul_f32 v[42:43], v[124:125], v[10:11] op_sel_hi:[0,1]
	v_pk_mul_f32 v[44:45], v[124:125], v[12:13] op_sel_hi:[0,1]
	v_pk_mul_f32 v[46:47], v[124:125], v[14:15] op_sel_hi:[0,1]
	v_pk_mul_f32 v[48:49], v[124:125], v[16:17] op_sel_hi:[0,1]
	v_pk_mul_f32 v[50:51], v[124:125], v[18:19] op_sel_hi:[0,1]
	v_pk_mul_f32 v[52:53], v[124:125], v[20:21] op_sel_hi:[0,1]
	v_pk_mul_f32 v[54:55], v[124:125], v[22:23] op_sel_hi:[0,1]
	v_pk_mul_f32 v[56:57], v[124:125], v[24:25] op_sel_hi:[0,1]
	v_pk_mul_f32 v[58:59], v[124:125], v[26:27] op_sel_hi:[0,1]
	v_pk_mul_f32 v[60:61], v[124:125], v[28:29] op_sel_hi:[0,1]
	v_pk_mul_f32 v[62:63], v[124:125], v[30:31] op_sel_hi:[0,1]
	v_cvt_scalef32_pk32_f32_fp6 v[0:31], v[146:151], 1.0
	v_pk_mul_f32 v[64:65], v[124:125], v[0:1] op_sel_hi:[0,1]
	v_pk_mul_f32 v[66:67], v[124:125], v[2:3] op_sel_hi:[0,1]
	v_pk_mul_f32 v[68:69], v[124:125], v[4:5] op_sel_hi:[0,1]
	v_pk_mul_f32 v[70:71], v[124:125], v[6:7] op_sel_hi:[0,1]
	v_pk_mul_f32 v[72:73], v[124:125], v[8:9] op_sel_hi:[0,1]
	v_pk_mul_f32 v[74:75], v[124:125], v[10:11] op_sel_hi:[0,1]
	v_pk_mul_f32 v[76:77], v[124:125], v[12:13] op_sel_hi:[0,1]
	v_pk_mul_f32 v[78:79], v[124:125], v[14:15] op_sel_hi:[0,1]
	v_pk_mul_f32 v[80:81], v[124:125], v[16:17] op_sel_hi:[0,1]
	v_pk_mul_f32 v[82:83], v[124:125], v[18:19] op_sel_hi:[0,1]
	v_pk_mul_f32 v[84:85], v[124:125], v[20:21] op_sel_hi:[0,1]
	v_pk_mul_f32 v[86:87], v[124:125], v[22:23] op_sel_hi:[0,1]
	v_pk_mul_f32 v[88:89], v[124:125], v[24:25] op_sel_hi:[0,1]
	v_pk_mul_f32 v[90:91], v[124:125], v[26:27] op_sel_hi:[0,1]
	v_pk_mul_f32 v[92:93], v[124:125], v[28:29] op_sel_hi:[0,1]
	v_pk_mul_f32 v[94:95], v[124:125], v[30:31] op_sel_hi:[0,1]
	global_load_dwordx2 v[96:97], v248, s[32:33]
	global_load_dwordx4 v[98:101], v249, s[58:59]
	v_mad_u32_u24 v241, v132, s52, v244
	global_load_dwordx4 v[140:143], v241, s[30:31]
	global_load_dwordx4 v[144:147], v241, s[30:31] offset:64
	global_load_dwordx4 v[148:151], v241, s[30:31] offset:128
	s_waitcnt vmcnt(24)
	v_cvt_scalef32_pk32_f32_fp6 v[0:31], v[152:157], 1.0
	v_pk_fma_f32 v[32:33], v[124:125], v[0:1], v[32:33] op_sel:[1,0,0] op_sel_hi:[1,1,1]
	v_pk_fma_f32 v[34:35], v[124:125], v[2:3], v[34:35] op_sel:[1,0,0] op_sel_hi:[1,1,1]
	v_pk_fma_f32 v[36:37], v[124:125], v[4:5], v[36:37] op_sel:[1,0,0] op_sel_hi:[1,1,1]
	v_pk_fma_f32 v[38:39], v[124:125], v[6:7], v[38:39] op_sel:[1,0,0] op_sel_hi:[1,1,1]
	v_pk_fma_f32 v[40:41], v[124:125], v[8:9], v[40:41] op_sel:[1,0,0] op_sel_hi:[1,1,1]
	v_pk_fma_f32 v[42:43], v[124:125], v[10:11], v[42:43] op_sel:[1,0,0] op_sel_hi:[1,1,1]
	v_pk_fma_f32 v[44:45], v[124:125], v[12:13], v[44:45] op_sel:[1,0,0] op_sel_hi:[1,1,1]
	v_pk_fma_f32 v[46:47], v[124:125], v[14:15], v[46:47] op_sel:[1,0,0] op_sel_hi:[1,1,1]
	v_pk_fma_f32 v[48:49], v[124:125], v[16:17], v[48:49] op_sel:[1,0,0] op_sel_hi:[1,1,1]
	v_pk_fma_f32 v[50:51], v[124:125], v[18:19], v[50:51] op_sel:[1,0,0] op_sel_hi:[1,1,1]
	v_pk_fma_f32 v[52:53], v[124:125], v[20:21], v[52:53] op_sel:[1,0,0] op_sel_hi:[1,1,1]
	v_pk_fma_f32 v[54:55], v[124:125], v[22:23], v[54:55] op_sel:[1,0,0] op_sel_hi:[1,1,1]
	v_pk_fma_f32 v[56:57], v[124:125], v[24:25], v[56:57] op_sel:[1,0,0] op_sel_hi:[1,1,1]
	v_pk_fma_f32 v[58:59], v[124:125], v[26:27], v[58:59] op_sel:[1,0,0] op_sel_hi:[1,1,1]
	v_pk_fma_f32 v[60:61], v[124:125], v[28:29], v[60:61] op_sel:[1,0,0] op_sel_hi:[1,1,1]
	v_pk_fma_f32 v[62:63], v[124:125], v[30:31], v[62:63] op_sel:[1,0,0] op_sel_hi:[1,1,1]
	v_cvt_scalef32_pk32_f32_fp6 v[0:31], v[158:163], 1.0
	v_pk_fma_f32 v[64:65], v[124:125], v[0:1], v[64:65] op_sel:[1,0,0] op_sel_hi:[1,1,1]
	v_pk_fma_f32 v[66:67], v[124:125], v[2:3], v[66:67] op_sel:[1,0,0] op_sel_hi:[1,1,1]
	v_pk_fma_f32 v[68:69], v[124:125], v[4:5], v[68:69] op_sel:[1,0,0] op_sel_hi:[1,1,1]
	v_pk_fma_f32 v[70:71], v[124:125], v[6:7], v[70:71] op_sel:[1,0,0] op_sel_hi:[1,1,1]
	v_pk_fma_f32 v[72:73], v[124:125], v[8:9], v[72:73] op_sel:[1,0,0] op_sel_hi:[1,1,1]
	v_pk_fma_f32 v[74:75], v[124:125], v[10:11], v[74:75] op_sel:[1,0,0] op_sel_hi:[1,1,1]
	v_pk_fma_f32 v[76:77], v[124:125], v[12:13], v[76:77] op_sel:[1,0,0] op_sel_hi:[1,1,1]
	v_pk_fma_f32 v[78:79], v[124:125], v[14:15], v[78:79] op_sel:[1,0,0] op_sel_hi:[1,1,1]
	v_pk_fma_f32 v[80:81], v[124:125], v[16:17], v[80:81] op_sel:[1,0,0] op_sel_hi:[1,1,1]
	v_pk_fma_f32 v[82:83], v[124:125], v[18:19], v[82:83] op_sel:[1,0,0] op_sel_hi:[1,1,1]
	v_pk_fma_f32 v[84:85], v[124:125], v[20:21], v[84:85] op_sel:[1,0,0] op_sel_hi:[1,1,1]
	v_pk_fma_f32 v[86:87], v[124:125], v[22:23], v[86:87] op_sel:[1,0,0] op_sel_hi:[1,1,1]
	v_pk_fma_f32 v[88:89], v[124:125], v[24:25], v[88:89] op_sel:[1,0,0] op_sel_hi:[1,1,1]
	v_pk_fma_f32 v[90:91], v[124:125], v[26:27], v[90:91] op_sel:[1,0,0] op_sel_hi:[1,1,1]
	v_pk_fma_f32 v[92:93], v[124:125], v[28:29], v[92:93] op_sel:[1,0,0] op_sel_hi:[1,1,1]
	v_pk_fma_f32 v[94:95], v[124:125], v[30:31], v[94:95] op_sel:[1,0,0] op_sel_hi:[1,1,1]
	v_mad_u32_u24 v241, v133, s52, v244
	global_load_dwordx4 v[152:155], v241, s[30:31]
	global_load_dwordx4 v[156:159], v241, s[30:31] offset:64
	global_load_dwordx4 v[160:163], v241, s[30:31] offset:128
	s_waitcnt vmcnt(24)
	v_cvt_scalef32_pk32_f32_fp6 v[0:31], v[164:169], 1.0
	v_pk_fma_f32 v[32:33], v[126:127], v[0:1], v[32:33] op_sel_hi:[0,1,1]
	v_pk_fma_f32 v[34:35], v[126:127], v[2:3], v[34:35] op_sel_hi:[0,1,1]
	v_pk_fma_f32 v[36:37], v[126:127], v[4:5], v[36:37] op_sel_hi:[0,1,1]
	v_pk_fma_f32 v[38:39], v[126:127], v[6:7], v[38:39] op_sel_hi:[0,1,1]
	v_pk_fma_f32 v[40:41], v[126:127], v[8:9], v[40:41] op_sel_hi:[0,1,1]
	v_pk_fma_f32 v[42:43], v[126:127], v[10:11], v[42:43] op_sel_hi:[0,1,1]
	v_pk_fma_f32 v[44:45], v[126:127], v[12:13], v[44:45] op_sel_hi:[0,1,1]
	v_pk_fma_f32 v[46:47], v[126:127], v[14:15], v[46:47] op_sel_hi:[0,1,1]
	v_pk_fma_f32 v[48:49], v[126:127], v[16:17], v[48:49] op_sel_hi:[0,1,1]
	v_pk_fma_f32 v[50:51], v[126:127], v[18:19], v[50:51] op_sel_hi:[0,1,1]
	v_pk_fma_f32 v[52:53], v[126:127], v[20:21], v[52:53] op_sel_hi:[0,1,1]
	v_pk_fma_f32 v[54:55], v[126:127], v[22:23], v[54:55] op_sel_hi:[0,1,1]
	v_pk_fma_f32 v[56:57], v[126:127], v[24:25], v[56:57] op_sel_hi:[0,1,1]
	v_pk_fma_f32 v[58:59], v[126:127], v[26:27], v[58:59] op_sel_hi:[0,1,1]
	v_pk_fma_f32 v[60:61], v[126:127], v[28:29], v[60:61] op_sel_hi:[0,1,1]
	v_pk_fma_f32 v[62:63], v[126:127], v[30:31], v[62:63] op_sel_hi:[0,1,1]
	v_cvt_scalef32_pk32_f32_fp6 v[0:31], v[170:175], 1.0
	v_pk_fma_f32 v[64:65], v[126:127], v[0:1], v[64:65] op_sel_hi:[0,1,1]
	v_pk_fma_f32 v[66:67], v[126:127], v[2:3], v[66:67] op_sel_hi:[0,1,1]
	v_pk_fma_f32 v[68:69], v[126:127], v[4:5], v[68:69] op_sel_hi:[0,1,1]
	v_pk_fma_f32 v[70:71], v[126:127], v[6:7], v[70:71] op_sel_hi:[0,1,1]
	v_pk_fma_f32 v[72:73], v[126:127], v[8:9], v[72:73] op_sel_hi:[0,1,1]
	v_pk_fma_f32 v[74:75], v[126:127], v[10:11], v[74:75] op_sel_hi:[0,1,1]
	v_pk_fma_f32 v[76:77], v[126:127], v[12:13], v[76:77] op_sel_hi:[0,1,1]
	v_pk_fma_f32 v[78:79], v[126:127], v[14:15], v[78:79] op_sel_hi:[0,1,1]
	v_pk_fma_f32 v[80:81], v[126:127], v[16:17], v[80:81] op_sel_hi:[0,1,1]
	v_pk_fma_f32 v[82:83], v[126:127], v[18:19], v[82:83] op_sel_hi:[0,1,1]
	v_pk_fma_f32 v[84:85], v[126:127], v[20:21], v[84:85] op_sel_hi:[0,1,1]
	v_pk_fma_f32 v[86:87], v[126:127], v[22:23], v[86:87] op_sel_hi:[0,1,1]
	v_pk_fma_f32 v[88:89], v[126:127], v[24:25], v[88:89] op_sel_hi:[0,1,1]
	v_pk_fma_f32 v[90:91], v[126:127], v[26:27], v[90:91] op_sel_hi:[0,1,1]
	v_pk_fma_f32 v[92:93], v[126:127], v[28:29], v[92:93] op_sel_hi:[0,1,1]
	v_pk_fma_f32 v[94:95], v[126:127], v[30:31], v[94:95] op_sel_hi:[0,1,1]
	v_mad_u32_u24 v241, v134, s52, v244
	global_load_dwordx4 v[164:167], v241, s[30:31]
	global_load_dwordx4 v[168:171], v241, s[30:31] offset:64
	global_load_dwordx4 v[172:175], v241, s[30:31] offset:128
	s_waitcnt vmcnt(24)
	v_cvt_scalef32_pk32_f32_fp6 v[0:31], v[176:181], 1.0
	v_pk_fma_f32 v[32:33], v[126:127], v[0:1], v[32:33] op_sel:[1,0,0] op_sel_hi:[1,1,1]
	v_pk_fma_f32 v[34:35], v[126:127], v[2:3], v[34:35] op_sel:[1,0,0] op_sel_hi:[1,1,1]
	v_pk_fma_f32 v[36:37], v[126:127], v[4:5], v[36:37] op_sel:[1,0,0] op_sel_hi:[1,1,1]
	v_pk_fma_f32 v[38:39], v[126:127], v[6:7], v[38:39] op_sel:[1,0,0] op_sel_hi:[1,1,1]
	v_pk_fma_f32 v[40:41], v[126:127], v[8:9], v[40:41] op_sel:[1,0,0] op_sel_hi:[1,1,1]
	v_pk_fma_f32 v[42:43], v[126:127], v[10:11], v[42:43] op_sel:[1,0,0] op_sel_hi:[1,1,1]
	v_pk_fma_f32 v[44:45], v[126:127], v[12:13], v[44:45] op_sel:[1,0,0] op_sel_hi:[1,1,1]
	v_pk_fma_f32 v[46:47], v[126:127], v[14:15], v[46:47] op_sel:[1,0,0] op_sel_hi:[1,1,1]
	v_pk_fma_f32 v[48:49], v[126:127], v[16:17], v[48:49] op_sel:[1,0,0] op_sel_hi:[1,1,1]
	v_pk_fma_f32 v[50:51], v[126:127], v[18:19], v[50:51] op_sel:[1,0,0] op_sel_hi:[1,1,1]
	v_pk_fma_f32 v[52:53], v[126:127], v[20:21], v[52:53] op_sel:[1,0,0] op_sel_hi:[1,1,1]
	v_pk_fma_f32 v[54:55], v[126:127], v[22:23], v[54:55] op_sel:[1,0,0] op_sel_hi:[1,1,1]
	v_pk_fma_f32 v[56:57], v[126:127], v[24:25], v[56:57] op_sel:[1,0,0] op_sel_hi:[1,1,1]
	v_pk_fma_f32 v[58:59], v[126:127], v[26:27], v[58:59] op_sel:[1,0,0] op_sel_hi:[1,1,1]
	v_pk_fma_f32 v[60:61], v[126:127], v[28:29], v[60:61] op_sel:[1,0,0] op_sel_hi:[1,1,1]
	v_pk_fma_f32 v[62:63], v[126:127], v[30:31], v[62:63] op_sel:[1,0,0] op_sel_hi:[1,1,1]
	v_cvt_scalef32_pk32_f32_fp6 v[0:31], v[182:187], 1.0
	v_pk_fma_f32 v[64:65], v[126:127], v[0:1], v[64:65] op_sel:[1,0,0] op_sel_hi:[1,1,1]
	v_pk_fma_f32 v[66:67], v[126:127], v[2:3], v[66:67] op_sel:[1,0,0] op_sel_hi:[1,1,1]
	v_pk_fma_f32 v[68:69], v[126:127], v[4:5], v[68:69] op_sel:[1,0,0] op_sel_hi:[1,1,1]
	v_pk_fma_f32 v[70:71], v[126:127], v[6:7], v[70:71] op_sel:[1,0,0] op_sel_hi:[1,1,1]
	v_pk_fma_f32 v[72:73], v[126:127], v[8:9], v[72:73] op_sel:[1,0,0] op_sel_hi:[1,1,1]
	v_pk_fma_f32 v[74:75], v[126:127], v[10:11], v[74:75] op_sel:[1,0,0] op_sel_hi:[1,1,1]
	v_pk_fma_f32 v[76:77], v[126:127], v[12:13], v[76:77] op_sel:[1,0,0] op_sel_hi:[1,1,1]
	v_pk_fma_f32 v[78:79], v[126:127], v[14:15], v[78:79] op_sel:[1,0,0] op_sel_hi:[1,1,1]
	v_pk_fma_f32 v[80:81], v[126:127], v[16:17], v[80:81] op_sel:[1,0,0] op_sel_hi:[1,1,1]
	v_pk_fma_f32 v[82:83], v[126:127], v[18:19], v[82:83] op_sel:[1,0,0] op_sel_hi:[1,1,1]
	v_pk_fma_f32 v[84:85], v[126:127], v[20:21], v[84:85] op_sel:[1,0,0] op_sel_hi:[1,1,1]
	v_pk_fma_f32 v[86:87], v[126:127], v[22:23], v[86:87] op_sel:[1,0,0] op_sel_hi:[1,1,1]
	v_pk_fma_f32 v[88:89], v[126:127], v[24:25], v[88:89] op_sel:[1,0,0] op_sel_hi:[1,1,1]
	v_pk_fma_f32 v[90:91], v[126:127], v[26:27], v[90:91] op_sel:[1,0,0] op_sel_hi:[1,1,1]
	v_pk_fma_f32 v[92:93], v[126:127], v[28:29], v[92:93] op_sel:[1,0,0] op_sel_hi:[1,1,1]
	v_pk_fma_f32 v[94:95], v[126:127], v[30:31], v[94:95] op_sel:[1,0,0] op_sel_hi:[1,1,1]
	v_mad_u32_u24 v241, v135, s52, v244
	global_load_dwordx4 v[176:179], v241, s[30:31]
	global_load_dwordx4 v[180:183], v241, s[30:31] offset:64
	global_load_dwordx4 v[184:187], v241, s[30:31] offset:128
	s_waitcnt vmcnt(24)
	v_cvt_scalef32_pk32_f32_fp6 v[0:31], v[188:193], 1.0
	v_pk_fma_f32 v[32:33], v[128:129], v[0:1], v[32:33] op_sel_hi:[0,1,1]
	v_pk_fma_f32 v[34:35], v[128:129], v[2:3], v[34:35] op_sel_hi:[0,1,1]
	v_pk_fma_f32 v[36:37], v[128:129], v[4:5], v[36:37] op_sel_hi:[0,1,1]
	v_pk_fma_f32 v[38:39], v[128:129], v[6:7], v[38:39] op_sel_hi:[0,1,1]
	v_pk_fma_f32 v[40:41], v[128:129], v[8:9], v[40:41] op_sel_hi:[0,1,1]
	v_pk_fma_f32 v[42:43], v[128:129], v[10:11], v[42:43] op_sel_hi:[0,1,1]
	v_pk_fma_f32 v[44:45], v[128:129], v[12:13], v[44:45] op_sel_hi:[0,1,1]
	v_pk_fma_f32 v[46:47], v[128:129], v[14:15], v[46:47] op_sel_hi:[0,1,1]
	v_pk_fma_f32 v[48:49], v[128:129], v[16:17], v[48:49] op_sel_hi:[0,1,1]
	v_pk_fma_f32 v[50:51], v[128:129], v[18:19], v[50:51] op_sel_hi:[0,1,1]
	v_pk_fma_f32 v[52:53], v[128:129], v[20:21], v[52:53] op_sel_hi:[0,1,1]
	v_pk_fma_f32 v[54:55], v[128:129], v[22:23], v[54:55] op_sel_hi:[0,1,1]
	v_pk_fma_f32 v[56:57], v[128:129], v[24:25], v[56:57] op_sel_hi:[0,1,1]
	v_pk_fma_f32 v[58:59], v[128:129], v[26:27], v[58:59] op_sel_hi:[0,1,1]
	v_pk_fma_f32 v[60:61], v[128:129], v[28:29], v[60:61] op_sel_hi:[0,1,1]
	v_pk_fma_f32 v[62:63], v[128:129], v[30:31], v[62:63] op_sel_hi:[0,1,1]
	v_cvt_scalef32_pk32_f32_fp6 v[0:31], v[194:199], 1.0
	v_pk_fma_f32 v[64:65], v[128:129], v[0:1], v[64:65] op_sel_hi:[0,1,1]
	v_pk_fma_f32 v[66:67], v[128:129], v[2:3], v[66:67] op_sel_hi:[0,1,1]
	v_pk_fma_f32 v[68:69], v[128:129], v[4:5], v[68:69] op_sel_hi:[0,1,1]
	v_pk_fma_f32 v[70:71], v[128:129], v[6:7], v[70:71] op_sel_hi:[0,1,1]
	v_pk_fma_f32 v[72:73], v[128:129], v[8:9], v[72:73] op_sel_hi:[0,1,1]
	v_pk_fma_f32 v[74:75], v[128:129], v[10:11], v[74:75] op_sel_hi:[0,1,1]
	v_pk_fma_f32 v[76:77], v[128:129], v[12:13], v[76:77] op_sel_hi:[0,1,1]
	v_pk_fma_f32 v[78:79], v[128:129], v[14:15], v[78:79] op_sel_hi:[0,1,1]
	v_pk_fma_f32 v[80:81], v[128:129], v[16:17], v[80:81] op_sel_hi:[0,1,1]
	v_pk_fma_f32 v[82:83], v[128:129], v[18:19], v[82:83] op_sel_hi:[0,1,1]
	v_pk_fma_f32 v[84:85], v[128:129], v[20:21], v[84:85] op_sel_hi:[0,1,1]
	v_pk_fma_f32 v[86:87], v[128:129], v[22:23], v[86:87] op_sel_hi:[0,1,1]
	v_pk_fma_f32 v[88:89], v[128:129], v[24:25], v[88:89] op_sel_hi:[0,1,1]
	v_pk_fma_f32 v[90:91], v[128:129], v[26:27], v[90:91] op_sel_hi:[0,1,1]
	v_pk_fma_f32 v[92:93], v[128:129], v[28:29], v[92:93] op_sel_hi:[0,1,1]
	v_pk_fma_f32 v[94:95], v[128:129], v[30:31], v[94:95] op_sel_hi:[0,1,1]
	v_mad_u32_u24 v241, v136, s52, v244
	global_load_dwordx4 v[188:191], v241, s[30:31]
	global_load_dwordx4 v[192:195], v241, s[30:31] offset:64
	global_load_dwordx4 v[196:199], v241, s[30:31] offset:128
	s_waitcnt vmcnt(24)
	v_cvt_scalef32_pk32_f32_fp6 v[0:31], v[200:205], 1.0
	v_pk_fma_f32 v[32:33], v[128:129], v[0:1], v[32:33] op_sel:[1,0,0] op_sel_hi:[1,1,1]
	v_pk_fma_f32 v[34:35], v[128:129], v[2:3], v[34:35] op_sel:[1,0,0] op_sel_hi:[1,1,1]
	v_pk_fma_f32 v[36:37], v[128:129], v[4:5], v[36:37] op_sel:[1,0,0] op_sel_hi:[1,1,1]
	v_pk_fma_f32 v[38:39], v[128:129], v[6:7], v[38:39] op_sel:[1,0,0] op_sel_hi:[1,1,1]
	v_pk_fma_f32 v[40:41], v[128:129], v[8:9], v[40:41] op_sel:[1,0,0] op_sel_hi:[1,1,1]
	v_pk_fma_f32 v[42:43], v[128:129], v[10:11], v[42:43] op_sel:[1,0,0] op_sel_hi:[1,1,1]
	v_pk_fma_f32 v[44:45], v[128:129], v[12:13], v[44:45] op_sel:[1,0,0] op_sel_hi:[1,1,1]
	v_pk_fma_f32 v[46:47], v[128:129], v[14:15], v[46:47] op_sel:[1,0,0] op_sel_hi:[1,1,1]
	v_pk_fma_f32 v[48:49], v[128:129], v[16:17], v[48:49] op_sel:[1,0,0] op_sel_hi:[1,1,1]
	v_pk_fma_f32 v[50:51], v[128:129], v[18:19], v[50:51] op_sel:[1,0,0] op_sel_hi:[1,1,1]
	v_pk_fma_f32 v[52:53], v[128:129], v[20:21], v[52:53] op_sel:[1,0,0] op_sel_hi:[1,1,1]
	v_pk_fma_f32 v[54:55], v[128:129], v[22:23], v[54:55] op_sel:[1,0,0] op_sel_hi:[1,1,1]
	v_pk_fma_f32 v[56:57], v[128:129], v[24:25], v[56:57] op_sel:[1,0,0] op_sel_hi:[1,1,1]
	v_pk_fma_f32 v[58:59], v[128:129], v[26:27], v[58:59] op_sel:[1,0,0] op_sel_hi:[1,1,1]
	v_pk_fma_f32 v[60:61], v[128:129], v[28:29], v[60:61] op_sel:[1,0,0] op_sel_hi:[1,1,1]
	v_pk_fma_f32 v[62:63], v[128:129], v[30:31], v[62:63] op_sel:[1,0,0] op_sel_hi:[1,1,1]
	v_cvt_scalef32_pk32_f32_fp6 v[0:31], v[206:211], 1.0
	v_pk_fma_f32 v[64:65], v[128:129], v[0:1], v[64:65] op_sel:[1,0,0] op_sel_hi:[1,1,1]
	v_pk_fma_f32 v[66:67], v[128:129], v[2:3], v[66:67] op_sel:[1,0,0] op_sel_hi:[1,1,1]
	v_pk_fma_f32 v[68:69], v[128:129], v[4:5], v[68:69] op_sel:[1,0,0] op_sel_hi:[1,1,1]
	v_pk_fma_f32 v[70:71], v[128:129], v[6:7], v[70:71] op_sel:[1,0,0] op_sel_hi:[1,1,1]
	v_pk_fma_f32 v[72:73], v[128:129], v[8:9], v[72:73] op_sel:[1,0,0] op_sel_hi:[1,1,1]
	v_pk_fma_f32 v[74:75], v[128:129], v[10:11], v[74:75] op_sel:[1,0,0] op_sel_hi:[1,1,1]
	v_pk_fma_f32 v[76:77], v[128:129], v[12:13], v[76:77] op_sel:[1,0,0] op_sel_hi:[1,1,1]
	v_pk_fma_f32 v[78:79], v[128:129], v[14:15], v[78:79] op_sel:[1,0,0] op_sel_hi:[1,1,1]
	v_pk_fma_f32 v[80:81], v[128:129], v[16:17], v[80:81] op_sel:[1,0,0] op_sel_hi:[1,1,1]
	v_pk_fma_f32 v[82:83], v[128:129], v[18:19], v[82:83] op_sel:[1,0,0] op_sel_hi:[1,1,1]
	v_pk_fma_f32 v[84:85], v[128:129], v[20:21], v[84:85] op_sel:[1,0,0] op_sel_hi:[1,1,1]
	v_pk_fma_f32 v[86:87], v[128:129], v[22:23], v[86:87] op_sel:[1,0,0] op_sel_hi:[1,1,1]
	v_pk_fma_f32 v[88:89], v[128:129], v[24:25], v[88:89] op_sel:[1,0,0] op_sel_hi:[1,1,1]
	v_pk_fma_f32 v[90:91], v[128:129], v[26:27], v[90:91] op_sel:[1,0,0] op_sel_hi:[1,1,1]
	v_pk_fma_f32 v[92:93], v[128:129], v[28:29], v[92:93] op_sel:[1,0,0] op_sel_hi:[1,1,1]
	v_pk_fma_f32 v[94:95], v[128:129], v[30:31], v[94:95] op_sel:[1,0,0] op_sel_hi:[1,1,1]
	v_mad_u32_u24 v241, v137, s52, v244
	global_load_dwordx4 v[200:203], v241, s[30:31]
	global_load_dwordx4 v[204:207], v241, s[30:31] offset:64
	global_load_dwordx4 v[208:211], v241, s[30:31] offset:128
	s_waitcnt vmcnt(24)
	v_cvt_scalef32_pk32_f32_fp6 v[0:31], v[212:217], 1.0
	v_pk_fma_f32 v[32:33], v[130:131], v[0:1], v[32:33] op_sel_hi:[0,1,1]
	v_pk_fma_f32 v[34:35], v[130:131], v[2:3], v[34:35] op_sel_hi:[0,1,1]
	v_pk_fma_f32 v[36:37], v[130:131], v[4:5], v[36:37] op_sel_hi:[0,1,1]
	v_pk_fma_f32 v[38:39], v[130:131], v[6:7], v[38:39] op_sel_hi:[0,1,1]
	v_pk_fma_f32 v[40:41], v[130:131], v[8:9], v[40:41] op_sel_hi:[0,1,1]
	v_pk_fma_f32 v[42:43], v[130:131], v[10:11], v[42:43] op_sel_hi:[0,1,1]
	v_pk_fma_f32 v[44:45], v[130:131], v[12:13], v[44:45] op_sel_hi:[0,1,1]
	v_pk_fma_f32 v[46:47], v[130:131], v[14:15], v[46:47] op_sel_hi:[0,1,1]
	v_pk_fma_f32 v[48:49], v[130:131], v[16:17], v[48:49] op_sel_hi:[0,1,1]
	v_pk_fma_f32 v[50:51], v[130:131], v[18:19], v[50:51] op_sel_hi:[0,1,1]
	v_pk_fma_f32 v[52:53], v[130:131], v[20:21], v[52:53] op_sel_hi:[0,1,1]
	v_pk_fma_f32 v[54:55], v[130:131], v[22:23], v[54:55] op_sel_hi:[0,1,1]
	v_pk_fma_f32 v[56:57], v[130:131], v[24:25], v[56:57] op_sel_hi:[0,1,1]
	v_pk_fma_f32 v[58:59], v[130:131], v[26:27], v[58:59] op_sel_hi:[0,1,1]
	v_pk_fma_f32 v[60:61], v[130:131], v[28:29], v[60:61] op_sel_hi:[0,1,1]
	v_pk_fma_f32 v[62:63], v[130:131], v[30:31], v[62:63] op_sel_hi:[0,1,1]
	v_cvt_scalef32_pk32_f32_fp6 v[0:31], v[218:223], 1.0
	v_pk_fma_f32 v[64:65], v[130:131], v[0:1], v[64:65] op_sel_hi:[0,1,1]
	v_pk_fma_f32 v[66:67], v[130:131], v[2:3], v[66:67] op_sel_hi:[0,1,1]
	v_pk_fma_f32 v[68:69], v[130:131], v[4:5], v[68:69] op_sel_hi:[0,1,1]
	v_pk_fma_f32 v[70:71], v[130:131], v[6:7], v[70:71] op_sel_hi:[0,1,1]
	v_pk_fma_f32 v[72:73], v[130:131], v[8:9], v[72:73] op_sel_hi:[0,1,1]
	v_pk_fma_f32 v[74:75], v[130:131], v[10:11], v[74:75] op_sel_hi:[0,1,1]
	v_pk_fma_f32 v[76:77], v[130:131], v[12:13], v[76:77] op_sel_hi:[0,1,1]
	v_pk_fma_f32 v[78:79], v[130:131], v[14:15], v[78:79] op_sel_hi:[0,1,1]
	v_pk_fma_f32 v[80:81], v[130:131], v[16:17], v[80:81] op_sel_hi:[0,1,1]
	v_pk_fma_f32 v[82:83], v[130:131], v[18:19], v[82:83] op_sel_hi:[0,1,1]
	v_pk_fma_f32 v[84:85], v[130:131], v[20:21], v[84:85] op_sel_hi:[0,1,1]
	v_pk_fma_f32 v[86:87], v[130:131], v[22:23], v[86:87] op_sel_hi:[0,1,1]
	v_pk_fma_f32 v[88:89], v[130:131], v[24:25], v[88:89] op_sel_hi:[0,1,1]
	v_pk_fma_f32 v[90:91], v[130:131], v[26:27], v[90:91] op_sel_hi:[0,1,1]
	v_pk_fma_f32 v[92:93], v[130:131], v[28:29], v[92:93] op_sel_hi:[0,1,1]
	v_pk_fma_f32 v[94:95], v[130:131], v[30:31], v[94:95] op_sel_hi:[0,1,1]
	v_mad_u32_u24 v241, v138, s52, v244
	global_load_dwordx4 v[212:215], v241, s[30:31]
	global_load_dwordx4 v[216:219], v241, s[30:31] offset:64
	global_load_dwordx4 v[220:223], v241, s[30:31] offset:128
	s_waitcnt vmcnt(24)
	v_cvt_scalef32_pk32_f32_fp6 v[0:31], v[224:229], 1.0
	v_pk_fma_f32 v[32:33], v[130:131], v[0:1], v[32:33] op_sel:[1,0,0] op_sel_hi:[1,1,1]
	v_pk_fma_f32 v[34:35], v[130:131], v[2:3], v[34:35] op_sel:[1,0,0] op_sel_hi:[1,1,1]
	v_pk_fma_f32 v[36:37], v[130:131], v[4:5], v[36:37] op_sel:[1,0,0] op_sel_hi:[1,1,1]
	v_pk_fma_f32 v[38:39], v[130:131], v[6:7], v[38:39] op_sel:[1,0,0] op_sel_hi:[1,1,1]
	v_pk_fma_f32 v[40:41], v[130:131], v[8:9], v[40:41] op_sel:[1,0,0] op_sel_hi:[1,1,1]
	v_pk_fma_f32 v[42:43], v[130:131], v[10:11], v[42:43] op_sel:[1,0,0] op_sel_hi:[1,1,1]
	v_pk_fma_f32 v[44:45], v[130:131], v[12:13], v[44:45] op_sel:[1,0,0] op_sel_hi:[1,1,1]
	v_pk_fma_f32 v[46:47], v[130:131], v[14:15], v[46:47] op_sel:[1,0,0] op_sel_hi:[1,1,1]
	v_pk_fma_f32 v[48:49], v[130:131], v[16:17], v[48:49] op_sel:[1,0,0] op_sel_hi:[1,1,1]
	v_pk_fma_f32 v[50:51], v[130:131], v[18:19], v[50:51] op_sel:[1,0,0] op_sel_hi:[1,1,1]
	v_pk_fma_f32 v[52:53], v[130:131], v[20:21], v[52:53] op_sel:[1,0,0] op_sel_hi:[1,1,1]
	v_pk_fma_f32 v[54:55], v[130:131], v[22:23], v[54:55] op_sel:[1,0,0] op_sel_hi:[1,1,1]
	v_pk_fma_f32 v[56:57], v[130:131], v[24:25], v[56:57] op_sel:[1,0,0] op_sel_hi:[1,1,1]
	v_pk_fma_f32 v[58:59], v[130:131], v[26:27], v[58:59] op_sel:[1,0,0] op_sel_hi:[1,1,1]
	v_pk_fma_f32 v[60:61], v[130:131], v[28:29], v[60:61] op_sel:[1,0,0] op_sel_hi:[1,1,1]
	v_pk_fma_f32 v[62:63], v[130:131], v[30:31], v[62:63] op_sel:[1,0,0] op_sel_hi:[1,1,1]
	v_cvt_scalef32_pk32_f32_fp6 v[0:31], v[230:235], 1.0
	v_pk_fma_f32 v[64:65], v[130:131], v[0:1], v[64:65] op_sel:[1,0,0] op_sel_hi:[1,1,1]
	v_pk_fma_f32 v[66:67], v[130:131], v[2:3], v[66:67] op_sel:[1,0,0] op_sel_hi:[1,1,1]
	v_pk_fma_f32 v[68:69], v[130:131], v[4:5], v[68:69] op_sel:[1,0,0] op_sel_hi:[1,1,1]
	v_pk_fma_f32 v[70:71], v[130:131], v[6:7], v[70:71] op_sel:[1,0,0] op_sel_hi:[1,1,1]
	v_pk_fma_f32 v[72:73], v[130:131], v[8:9], v[72:73] op_sel:[1,0,0] op_sel_hi:[1,1,1]
	v_pk_fma_f32 v[74:75], v[130:131], v[10:11], v[74:75] op_sel:[1,0,0] op_sel_hi:[1,1,1]
	v_pk_fma_f32 v[76:77], v[130:131], v[12:13], v[76:77] op_sel:[1,0,0] op_sel_hi:[1,1,1]
	v_pk_fma_f32 v[78:79], v[130:131], v[14:15], v[78:79] op_sel:[1,0,0] op_sel_hi:[1,1,1]
	v_pk_fma_f32 v[80:81], v[130:131], v[16:17], v[80:81] op_sel:[1,0,0] op_sel_hi:[1,1,1]
	v_pk_fma_f32 v[82:83], v[130:131], v[18:19], v[82:83] op_sel:[1,0,0] op_sel_hi:[1,1,1]
	v_pk_fma_f32 v[84:85], v[130:131], v[20:21], v[84:85] op_sel:[1,0,0] op_sel_hi:[1,1,1]
	v_pk_fma_f32 v[86:87], v[130:131], v[22:23], v[86:87] op_sel:[1,0,0] op_sel_hi:[1,1,1]
	v_pk_fma_f32 v[88:89], v[130:131], v[24:25], v[88:89] op_sel:[1,0,0] op_sel_hi:[1,1,1]
	v_pk_fma_f32 v[90:91], v[130:131], v[26:27], v[90:91] op_sel:[1,0,0] op_sel_hi:[1,1,1]
	v_pk_fma_f32 v[92:93], v[130:131], v[28:29], v[92:93] op_sel:[1,0,0] op_sel_hi:[1,1,1]
	v_pk_fma_f32 v[94:95], v[130:131], v[30:31], v[94:95] op_sel:[1,0,0] op_sel_hi:[1,1,1]
	v_mad_u32_u24 v241, v139, s52, v244
	global_load_dwordx4 v[224:227], v241, s[30:31]
	global_load_dwordx4 v[228:231], v241, s[30:31] offset:64
	global_load_dwordx4 v[232:235], v241, s[30:31] offset:128
	s_mov_b32 s86, s78
	s_mov_b32 s87, s79
	s_mov_b32 s88, s80
	s_mov_b32 s78, s60
	s_mov_b32 s79, s61
	s_mov_b32 s80, s57
	s_mov_b32 s7, s53
	s_mov_b32 s8, s54
	s_add_i32 s53, s7, 1
	s_mov_b32 s54, s8
	s_cmp_eq_u32 s53, 8
	s_cselect_b32 s53, 0, s53
	s_cselect_b32 s34, 1, 0
	s_add_i32 s54, s54, s34
	s_mul_i32 s55, s53, s5
	s_add_i32 s55, s55, s6
	s_min_u32 s55, s55, 0x3fff
	s_and_b32 s34, s54, 7
	s_mul_i32 s34, s34, 0x300000
	s_cmp_lt_u32 s54, 8
	s_cselect_b32 s30, s16, s18
	s_cselect_b32 s31, s17, s19
	s_add_u32 s30, s30, s34
	s_addc_u32 s31, s31, 0
	s_and_b32 s34, s54, 7
	s_lshl_b32 s34, s34, 6
	s_lshl_b32 s35, s55, 12
	s_add_u32 s34, s34, s35
	s_add_u32 s32, s24, s34
	s_addc_u32 s33, s25, 0
	s_and_b32 s34, s54, 7
	s_lshl_b32 s34, s34, 7
	s_lshr_b32 s35, s55, 13
	s_mul_i32 s35, s35, 0xc000
	s_add_u32 s35, s35, s34
	s_add_u32 s35, s35, 0xa000
	s_add_u32 s58, s26, s35
	s_addc_u32 s59, s27, 0
	s_lshl_b32 s35, s55, 13
	s_add_u32 s35, s35, s34
	s_add_u32 s60, s28, s35
	s_addc_u32 s61, s29, 0
	s_mul_i32 s34, s53, s5
	s_add_i32 s34, s34, s6
	s_cmp_lt_u32 s34, 0x4000
	s_cselect_b32 s57, 1, 0
	s_lshl_b32 s34, s53, 9
	v_add_u32_e32 v240, s34, v246
	ds_read_b128 v[132:135], v240
	ds_read_b128 v[136:139], v240 offset:16
	v_cndmask_b32_e64 v236, v64, v32, s[46:47]
	v_cndmask_b32_e64 v237, v32, v64, s[46:47]
	v_cndmask_b32_e64 v238, v65, v33, s[46:47]
	v_cndmask_b32_e64 v239, v33, v65, s[46:47]
	v_add_f32_dpp v32, v236, v237 row_ror:8 row_mask:0xf bank_mask:0xf
	v_add_f32_dpp v33, v238, v239 row_ror:8 row_mask:0xf bank_mask:0xf
	v_cndmask_b32_e64 v236, v66, v34, s[46:47]
	v_cndmask_b32_e64 v237, v34, v66, s[46:47]
	v_cndmask_b32_e64 v238, v67, v35, s[46:47]
	v_cndmask_b32_e64 v239, v35, v67, s[46:47]
	v_add_f32_dpp v34, v236, v237 row_ror:8 row_mask:0xf bank_mask:0xf
	v_add_f32_dpp v35, v238, v239 row_ror:8 row_mask:0xf bank_mask:0xf
	v_cndmask_b32_e64 v236, v68, v36, s[46:47]
	v_cndmask_b32_e64 v237, v36, v68, s[46:47]
	v_cndmask_b32_e64 v238, v69, v37, s[46:47]
	v_cndmask_b32_e64 v239, v37, v69, s[46:47]
	v_add_f32_dpp v36, v236, v237 row_ror:8 row_mask:0xf bank_mask:0xf
	v_add_f32_dpp v37, v238, v239 row_ror:8 row_mask:0xf bank_mask:0xf
	v_cndmask_b32_e64 v236, v70, v38, s[46:47]
	v_cndmask_b32_e64 v237, v38, v70, s[46:47]
	v_cndmask_b32_e64 v238, v71, v39, s[46:47]
	v_cndmask_b32_e64 v239, v39, v71, s[46:47]
	v_add_f32_dpp v38, v236, v237 row_ror:8 row_mask:0xf bank_mask:0xf
	v_add_f32_dpp v39, v238, v239 row_ror:8 row_mask:0xf bank_mask:0xf
	v_cndmask_b32_e64 v236, v72, v40, s[46:47]
	v_cndmask_b32_e64 v237, v40, v72, s[46:47]
	v_cndmask_b32_e64 v238, v73, v41, s[46:47]
	v_cndmask_b32_e64 v239, v41, v73, s[46:47]
	v_add_f32_dpp v40, v236, v237 row_ror:8 row_mask:0xf bank_mask:0xf
	v_add_f32_dpp v41, v238, v239 row_ror:8 row_mask:0xf bank_mask:0xf
	v_cndmask_b32_e64 v236, v74, v42, s[46:47]
	v_cndmask_b32_e64 v237, v42, v74, s[46:47]
	v_cndmask_b32_e64 v238, v75, v43, s[46:47]
	v_cndmask_b32_e64 v239, v43, v75, s[46:47]
	v_add_f32_dpp v42, v236, v237 row_ror:8 row_mask:0xf bank_mask:0xf
	v_add_f32_dpp v43, v238, v239 row_ror:8 row_mask:0xf bank_mask:0xf
	v_cndmask_b32_e64 v236, v76, v44, s[46:47]
	v_cndmask_b32_e64 v237, v44, v76, s[46:47]
	v_cndmask_b32_e64 v238, v77, v45, s[46:47]
	v_cndmask_b32_e64 v239, v45, v77, s[46:47]
	v_add_f32_dpp v44, v236, v237 row_ror:8 row_mask:0xf bank_mask:0xf
	v_add_f32_dpp v45, v238, v239 row_ror:8 row_mask:0xf bank_mask:0xf
	v_cndmask_b32_e64 v236, v78, v46, s[46:47]
	v_cndmask_b32_e64 v237, v46, v78, s[46:47]
	v_cndmask_b32_e64 v238, v79, v47, s[46:47]
	v_cndmask_b32_e64 v239, v47, v79, s[46:47]
	v_add_f32_dpp v46, v236, v237 row_ror:8 row_mask:0xf bank_mask:0xf
	v_add_f32_dpp v47, v238, v239 row_ror:8 row_mask:0xf bank_mask:0xf
	v_cndmask_b32_e64 v236, v80, v48, s[46:47]
	v_cndmask_b32_e64 v237, v48, v80, s[46:47]
	v_cndmask_b32_e64 v238, v81, v49, s[46:47]
	v_cndmask_b32_e64 v239, v49, v81, s[46:47]
	v_add_f32_dpp v48, v236, v237 row_ror:8 row_mask:0xf bank_mask:0xf
	v_add_f32_dpp v49, v238, v239 row_ror:8 row_mask:0xf bank_mask:0xf
	v_cndmask_b32_e64 v236, v82, v50, s[46:47]
	v_cndmask_b32_e64 v237, v50, v82, s[46:47]
	v_cndmask_b32_e64 v238, v83, v51, s[46:47]
	v_cndmask_b32_e64 v239, v51, v83, s[46:47]
	v_add_f32_dpp v50, v236, v237 row_ror:8 row_mask:0xf bank_mask:0xf
	v_add_f32_dpp v51, v238, v239 row_ror:8 row_mask:0xf bank_mask:0xf
	v_cndmask_b32_e64 v236, v84, v52, s[46:47]
	v_cndmask_b32_e64 v237, v52, v84, s[46:47]
	v_cndmask_b32_e64 v238, v85, v53, s[46:47]
	v_cndmask_b32_e64 v239, v53, v85, s[46:47]
	v_add_f32_dpp v52, v236, v237 row_ror:8 row_mask:0xf bank_mask:0xf
	v_add_f32_dpp v53, v238, v239 row_ror:8 row_mask:0xf bank_mask:0xf
	v_cndmask_b32_e64 v236, v86, v54, s[46:47]
	v_cndmask_b32_e64 v237, v54, v86, s[46:47]
	v_cndmask_b32_e64 v238, v87, v55, s[46:47]
	v_cndmask_b32_e64 v239, v55, v87, s[46:47]
	v_add_f32_dpp v54, v236, v237 row_ror:8 row_mask:0xf bank_mask:0xf
	v_add_f32_dpp v55, v238, v239 row_ror:8 row_mask:0xf bank_mask:0xf
	v_cndmask_b32_e64 v236, v88, v56, s[46:47]
	v_cndmask_b32_e64 v237, v56, v88, s[46:47]
	v_cndmask_b32_e64 v238, v89, v57, s[46:47]
	v_cndmask_b32_e64 v239, v57, v89, s[46:47]
	v_add_f32_dpp v56, v236, v237 row_ror:8 row_mask:0xf bank_mask:0xf
	v_add_f32_dpp v57, v238, v239 row_ror:8 row_mask:0xf bank_mask:0xf
	v_cndmask_b32_e64 v236, v90, v58, s[46:47]
	v_cndmask_b32_e64 v237, v58, v90, s[46:47]
	v_cndmask_b32_e64 v238, v91, v59, s[46:47]
	v_cndmask_b32_e64 v239, v59, v91, s[46:47]
	v_add_f32_dpp v58, v236, v237 row_ror:8 row_mask:0xf bank_mask:0xf
	v_add_f32_dpp v59, v238, v239 row_ror:8 row_mask:0xf bank_mask:0xf
	v_cndmask_b32_e64 v236, v92, v60, s[46:47]
	v_cndmask_b32_e64 v237, v60, v92, s[46:47]
	v_cndmask_b32_e64 v238, v93, v61, s[46:47]
	v_cndmask_b32_e64 v239, v61, v93, s[46:47]
	v_add_f32_dpp v60, v236, v237 row_ror:8 row_mask:0xf bank_mask:0xf
	v_add_f32_dpp v61, v238, v239 row_ror:8 row_mask:0xf bank_mask:0xf
	v_cndmask_b32_e64 v236, v94, v62, s[46:47]
	v_cndmask_b32_e64 v237, v62, v94, s[46:47]
	v_cndmask_b32_e64 v238, v95, v63, s[46:47]
	v_cndmask_b32_e64 v239, v63, v95, s[46:47]
	v_add_f32_dpp v62, v236, v237 row_ror:8 row_mask:0xf bank_mask:0xf
	v_add_f32_dpp v63, v238, v239 row_ror:8 row_mask:0xf bank_mask:0xf
	v_cndmask_b32_e64 v0, v48, v32, s[44:45]
	v_cndmask_b32_e64 v32, v32, v48, s[44:45]
	v_cndmask_b32_e64 v1, v49, v33, s[44:45]
	v_cndmask_b32_e64 v33, v33, v49, s[44:45]
	v_cndmask_b32_e64 v2, v50, v34, s[44:45]
	v_cndmask_b32_e64 v34, v34, v50, s[44:45]
	v_cndmask_b32_e64 v3, v51, v35, s[44:45]
	v_cndmask_b32_e64 v35, v35, v51, s[44:45]
	v_cndmask_b32_e64 v4, v52, v36, s[44:45]
	v_cndmask_b32_e64 v36, v36, v52, s[44:45]
	v_cndmask_b32_e64 v5, v53, v37, s[44:45]
	v_cndmask_b32_e64 v37, v37, v53, s[44:45]
	v_cndmask_b32_e64 v6, v54, v38, s[44:45]
	v_cndmask_b32_e64 v38, v38, v54, s[44:45]
	v_cndmask_b32_e64 v7, v55, v39, s[44:45]
	v_cndmask_b32_e64 v39, v39, v55, s[44:45]
	v_cndmask_b32_e64 v8, v56, v40, s[44:45]
	v_cndmask_b32_e64 v40, v40, v56, s[44:45]
	v_cndmask_b32_e64 v9, v57, v41, s[44:45]
	v_cndmask_b32_e64 v41, v41, v57, s[44:45]
	v_cndmask_b32_e64 v10, v58, v42, s[44:45]
	v_cndmask_b32_e64 v42, v42, v58, s[44:45]
	v_cndmask_b32_e64 v11, v59, v43, s[44:45]
	v_cndmask_b32_e64 v43, v43, v59, s[44:45]
	v_cndmask_b32_e64 v12, v60, v44, s[44:45]
	v_cndmask_b32_e64 v44, v44, v60, s[44:45]
	v_cndmask_b32_e64 v13, v61, v45, s[44:45]
	v_cndmask_b32_e64 v45, v45, v61, s[44:45]
	v_cndmask_b32_e64 v14, v62, v46, s[44:45]
	v_cndmask_b32_e64 v46, v46, v62, s[44:45]
	v_cndmask_b32_e64 v15, v63, v47, s[44:45]
	v_cndmask_b32_e64 v47, v47, v63, s[44:45]
	ds_swizzle_b32 v0, v0 offset:0x101f
	ds_swizzle_b32 v1, v1 offset:0x101f
	ds_swizzle_b32 v2, v2 offset:0x101f
	ds_swizzle_b32 v3, v3 offset:0x101f
	ds_swizzle_b32 v4, v4 offset:0x101f
	ds_swizzle_b32 v5, v5 offset:0x101f
	ds_swizzle_b32 v6, v6 offset:0x101f
	ds_swizzle_b32 v7, v7 offset:0x101f
	ds_swizzle_b32 v8, v8 offset:0x101f
	ds_swizzle_b32 v9, v9 offset:0x101f
	ds_swizzle_b32 v10, v10 offset:0x101f
	ds_swizzle_b32 v11, v11 offset:0x101f
	ds_swizzle_b32 v12, v12 offset:0x101f
	ds_swizzle_b32 v13, v13 offset:0x101f
	ds_swizzle_b32 v14, v14 offset:0x101f
	ds_swizzle_b32 v15, v15 offset:0x101f
	s_waitcnt lgkmcnt(0)
	v_add_f32_e32 v32, v32, v0
	v_add_f32_e32 v33, v33, v1
	v_add_f32_e32 v34, v34, v2
	v_add_f32_e32 v35, v35, v3
	v_add_f32_e32 v36, v36, v4
	v_add_f32_e32 v37, v37, v5
	v_add_f32_e32 v38, v38, v6
	v_add_f32_e32 v39, v39, v7
	v_add_f32_e32 v40, v40, v8
	v_add_f32_e32 v41, v41, v9
	v_add_f32_e32 v42, v42, v10
	v_add_f32_e32 v43, v43, v11
	v_add_f32_e32 v44, v44, v12
	v_add_f32_e32 v45, v45, v13
	v_add_f32_e32 v46, v46, v14
	v_add_f32_e32 v47, v47, v15
	v_cndmask_b32_e64 v0, v40, v32, s[48:49]
	v_cndmask_b32_e64 v32, v32, v40, s[48:49]
	v_cndmask_b32_e64 v1, v41, v33, s[48:49]
	v_cndmask_b32_e64 v33, v33, v41, s[48:49]
	v_cndmask_b32_e64 v2, v42, v34, s[48:49]
	v_cndmask_b32_e64 v34, v34, v42, s[48:49]
	v_cndmask_b32_e64 v3, v43, v35, s[48:49]
	v_cndmask_b32_e64 v35, v35, v43, s[48:49]
	v_cndmask_b32_e64 v4, v44, v36, s[48:49]
	v_cndmask_b32_e64 v36, v36, v44, s[48:49]
	v_cndmask_b32_e64 v5, v45, v37, s[48:49]
	v_cndmask_b32_e64 v37, v37, v45, s[48:49]
	v_cndmask_b32_e64 v6, v46, v38, s[48:49]
	v_cndmask_b32_e64 v38, v38, v46, s[48:49]
	v_cndmask_b32_e64 v7, v47, v39, s[48:49]
	v_cndmask_b32_e64 v39, v39, v47, s[48:49]
	ds_swizzle_b32 v0, v0 offset:0x401f
	ds_swizzle_b32 v1, v1 offset:0x401f
	ds_swizzle_b32 v2, v2 offset:0x401f
	ds_swizzle_b32 v3, v3 offset:0x401f
	ds_swizzle_b32 v4, v4 offset:0x401f
	ds_swizzle_b32 v5, v5 offset:0x401f
	ds_swizzle_b32 v6, v6 offset:0x401f
	ds_swizzle_b32 v7, v7 offset:0x401f
	s_waitcnt lgkmcnt(0)
	v_add_f32_e32 v32, v32, v0
	v_add_f32_e32 v33, v33, v1
	v_add_f32_e32 v34, v34, v2
	v_add_f32_e32 v35, v35, v3
	v_add_f32_e32 v36, v36, v4
	v_add_f32_e32 v37, v37, v5
	v_add_f32_e32 v38, v38, v6
	v_add_f32_e32 v39, v39, v7
	v_cndmask_b32_e64 v0, v36, v32, s[50:51]
	v_cndmask_b32_e64 v32, v32, v36, s[50:51]
	v_cndmask_b32_e64 v1, v37, v33, s[50:51]
	v_cndmask_b32_e64 v33, v33, v37, s[50:51]
	v_cndmask_b32_e64 v2, v38, v34, s[50:51]
	v_cndmask_b32_e64 v34, v34, v38, s[50:51]
	v_cndmask_b32_e64 v3, v39, v35, s[50:51]
	v_cndmask_b32_e64 v35, v35, v39, s[50:51]
	ds_bpermute_b32 v0, v250, v0
	ds_bpermute_b32 v1, v250, v1
	ds_bpermute_b32 v2, v250, v2
	ds_bpermute_b32 v3, v250, v3
	s_waitcnt lgkmcnt(0)
	v_add_f32_e32 v32, v32, v0
	v_add_f32_e32 v33, v33, v1
	v_add_f32_e32 v34, v34, v2
	v_add_f32_e32 v35, v35, v3
	v_lshlrev_b32_e32 v8, 16, v102
	v_and_b32_e32 v9, 0xffff0000, v102
	v_lshlrev_b32_e32 v10, 16, v103
	v_and_b32_e32 v11, 0xffff0000, v103
	v_pk_fma_f32 v[8:9], v[104:105], v[32:33], v[8:9]
	v_pk_fma_f32 v[10:11], v[106:107], v[34:35], v[10:11]
	s_cmp_eq_u32 s88, 0
	s_cbranch_scc1 .Lex_vskip
	global_store_dwordx4 v249, v[8:11], s[86:87]
	s_branch .Lex_vdone
.Lex_vskip:
	global_load_dword v108, v254, s[28:29]
